# KDT chunk operand also stored fragment-major (lane-contiguous chunkrec loads)
# speedup vs baseline: 1.0214x; 1.0058x over previous
; DI void phase_dn_chunkrec(PrmC p, unsigned char* smem) {
;     ...
;         f32x4 Sacc[2];
;         Sacc[0] = (f32x4){0.f, 0.f, 0.f, 0.f}; Sacc[1] = Sacc[0];
;         __syncthreads();
;         for (int i = tid; i < 32 * DS_PITCH / 16; i += NTHR) *(uint4*)(smem + D_ST + i * 16) = make_uint4(0, 0, 0, 0);
;         uint4 wf0, wf1, wf2, wf3, qf0, qf1, qf2, qf3, qk0, qk1, kd00, kd01, kd10, kd11; uint2 uf;
;         uint4 nwf0, nwf1, nwf2, nwf3, nqf0, nqf1, nqf2, nqf3, nqk0, nqk1, nkd00, nkd01, nkd10, nkd11; uint2 nuf;
;     ...
;         if (tid < 36) ((float*)(smem + D_EG))[tid] = DEG[(size_t)dir * 1152 + bh * 36 + DC_CIDX(tid)];
;         DC_LOAD(0, );
;         __syncthreads();
; #pragma unroll 1
;         for (int ch = 0; ch < 36; ++ch) {
.LBB0_301:
	s_or_b64 exec, exec, s[20:21]
	s_cmp_eq_u32 s31, 0
	s_cselect_b64 s[16:17], -1, 0
	s_and_b64 s[18:19], s[16:17], exec
	v_lshl_add_u64 v[142:143], v[60:61], 0, v[58:59]
	s_cselect_b32 s18, 0, 3
	v_or_b32_e32 v58, s18, v142
	v_mov_b32_e32 v59, v143
	v_lshlrev_b64 v[60:61], 13, v[58:59]
	v_lshl_add_u64 v[62:63], v[60:61], 0, v[166:167]
	v_lshl_add_u64 v[60:61], v[60:61], 0, v[138:139]
	v_lshlrev_b64 v[62:63], 1, v[62:63]
	v_lshl_add_u64 v[2:3], v[134:135], 0, v[62:63]
	v_lshl_add_u64 v[64:65], v[126:127], 0, v[62:63]
	v_lshl_add_u64 v[62:63], v[128:129], 0, v[62:63]
	global_load_dwordx4 v[114:117], v[64:65], off
	global_load_dwordx4 v[106:109], v[64:65], off offset:1024
	global_load_dwordx4 v[110:113], v[64:65], off offset:2048
	global_load_dwordx4 v[98:101], v[64:65], off offset:3072
	global_load_dwordx4 v[118:121], v[62:63], off
	global_load_dwordx4 v[102:105], v[62:63], off offset:1024
	global_load_dwordx4 v[94:97], v[62:63], off offset:2048
	global_load_dwordx4 v[90:93], v[62:63], off offset:3072
	v_lshl_add_u64 v[60:61], v[130:131], 0, v[60:61]
	v_lshlrev_b64 v[58:59], 7, v[58:59]
	s_lshl_b32 s18, s37, 5
	global_load_dwordx4 v[86:89], v[60:61], off
	global_load_dwordx4 v[82:85], v[60:61], off offset:64
	v_lshl_add_u64 v[60:61], v[58:59], 0, v[132:133]
	s_and_b32 s18, s18, 0x60
	v_lshlrev_b64 v[60:61], 7, v[60:61]
	v_or_b32_e32 v144, s18, v125
	v_lshl_add_u64 v[60:61], v[134:135], 0, v[60:61]
	v_or_b32_e32 v58, v58, v144
	global_load_dwordx4 v[70:73], v[2:3], off
	global_load_dwordx4 v[78:81], v[2:3], off offset:1024
	global_load_dwordx4 v[74:77], v[2:3], off offset:2048
	global_load_dwordx4 v[66:69], v[2:3], off offset:3072
	v_lshlrev_b64 v[58:59], 7, v[58:59]
	v_lshl_add_u64 v[58:59], v[136:137], 0, v[58:59]
	global_load_dwordx2 v[148:149], v[58:59], off
	s_lshl_b32 s18, s18, 1
	s_add_u32 s20, s27, s18
	s_addc_u32 s21, s28, 0
	s_lshl_b32 s29, s29, 8
	s_add_u32 s20, s20, s29
	s_addc_u32 s21, s21, 0
	s_lshl_b32 s37, s30, 8
	v_mov_b32_e32 v58, 0
	s_mov_b32 s39, 0
	s_mul_i32 s18, s31, 0x4800
	s_mov_b32 s19, s36
	v_lshl_add_u64 v[146:147], s[20:21], 0, v[0:1]
	s_lshl_b32 s29, s30, 11
	s_addk_i32 s37, 0x4000
	v_mov_b32_e32 v59, v58
	v_mov_b32_e32 v60, v58
	v_mov_b32_e32 v61, v58
	v_mov_b32_e32 v62, v58
	v_mov_b32_e32 v63, v58
	v_mov_b32_e32 v64, v58
	v_mov_b32_e32 v65, v58
	s_waitcnt lgkmcnt(0)
	s_barrier
	s_add_i32 s38, s39, 1
	s_cmp_eq_u32 s39, 35
	s_cbranch_scc1 .LBB0_308
	s_branch .LBB0_303

.LBB0_307:
	s_mov_b32 s21, s36
	v_lshl_add_u64 v[42:43], v[142:143], 0, s[20:21]
	v_lshlrev_b64 v[2:3], 13, v[42:43]
	v_lshl_add_u64 v[34:35], v[2:3], 0, v[138:139]
	v_lshl_add_u64 v[2:3], v[2:3], 0, v[166:167]
	v_lshlrev_b64 v[2:3], 1, v[2:3]
	v_lshl_add_u64 v[14:15], v[126:127], 0, v[2:3]
	v_lshl_add_u64 v[30:31], v[128:129], 0, v[2:3]
	v_lshl_add_u64 v[54:55], v[134:135], 0, v[2:3]
	global_load_dwordx4 v[2:5], v[14:15], off
	global_load_dwordx4 v[6:9], v[14:15], off offset:1024
	global_load_dwordx4 v[10:13], v[14:15], off offset:2048
	s_nop 0
	global_load_dwordx4 v[14:17], v[14:15], off offset:3072
	s_nop 0
	global_load_dwordx4 v[18:21], v[30:31], off
	global_load_dwordx4 v[22:25], v[30:31], off offset:1024
	global_load_dwordx4 v[26:29], v[30:31], off offset:2048
	s_nop 0
	global_load_dwordx4 v[30:33], v[30:31], off offset:3072
	v_lshlrev_b64 v[140:141], 7, v[42:43]
	v_lshl_add_u64 v[42:43], v[140:141], 0, v[132:133]
	v_lshlrev_b64 v[42:43], 7, v[42:43]
	v_lshl_add_u64 v[38:39], v[130:131], 0, v[34:35]
	v_or_b32_e32 v140, v140, v144
	global_load_dwordx4 v[34:37], v[38:39], off
	s_nop 0
	global_load_dwordx4 v[38:41], v[38:39], off offset:64
	s_nop 0
	global_load_dwordx4 v[42:45], v[54:55], off
	global_load_dwordx4 v[46:49], v[54:55], off offset:1024
	global_load_dwordx4 v[50:53], v[54:55], off offset:2048
	s_nop 0
	global_load_dwordx4 v[54:57], v[54:55], off offset:3072
	v_lshlrev_b64 v[140:141], 7, v[140:141]
	v_lshl_add_u64 v[140:141], v[136:137], 0, v[140:141]
	global_load_dwordx2 v[140:141], v[140:141], off

; DI unsigned pk2(float lo, float hi) { return f2bf(lo) | (f2bf(hi) << 16); }
; template <int D> DI void dn_out(float (&x)[64], lf_t Kl, lf_t Ql, lf_t Gn, bf16_t* DW, bf16_t* DQE, bf16_t* DKT, bf16_t* DUT, float* DEG, int item, int t) {
;     ...
;             for (int i = 0; i < 4; ++i) { const int idx = t + 256 * i, pi = idx >> 4, seg = idx & 15, n = D ? 63 - pi : pi; const float e = __expf(Gd[n]);
;                 const float4 a0 = *(const float4*)(Ql + n * 132 + seg * 8), a1 = *(const float4*)(Ql + n * 132 + seg * 8 + 4);
;                 uint4 o; o.x = pk2(a0.x * e, a0.y * e); o.y = pk2(a0.z * e, a0.w * e); o.z = pk2(a1.x * e, a1.y * e); o.w = pk2(a1.z * e, a1.w * e);
;                 *(uint4*)(DQE + (((size_t)D * 1152 + item) * 64 + pi) * 128 + seg * 8) = o; }
.LBB0_659:
	s_or_b64 exec, exec, s[44:45]
	v_ashrrev_i32_e32 v16, 4, v4
	v_lshlrev_b32_e32 v6, 2, v16
	v_sub_u32_e32 v6, v104, v6
	v_lshlrev_b32_e32 v0, 3, v4
	ds_read_b32 v12, v6 offset:508
	v_and_b32_e32 v0, 0x78, v0
	v_lshl_add_u32 v10, v0, 2, v103
	v_lshl_add_u64 v[6:7], s[86:87], 0, v[8:9]
	v_lshlrev_b32_e32 v0, 5, v0
	v_lshl_add_u64 v[92:93], v[6:7], 0, v[0:1]
	v_sub_u32_e32 v6, 63, v16
	v_mad_u64_u32 v[6:7], s[20:21], v6, s84, v[10:11]
	s_waitcnt lgkmcnt(0)
	v_mul_f32_e32 v0, 0x3fb8aa3b, v12
	ds_read_b128 v[12:15], v6
	v_exp_f32_e32 v0, v0
	v_ashrrev_i32_e32 v17, 31, v16
	v_and_b32_e32 v84, 15, v16
	v_lshrrev_b32_e32 v85, 4, v16
	v_lshlrev_b32_e32 v84, 4, v84
	v_lshl_add_u32 v84, v85, 12, v84
	v_mov_b32_e32 v85, 0
	v_lshl_add_u64 v[94:95], v[92:93], 0, v[84:85]
	ds_read_b128 v[84:87], v6 offset:16
	s_waitcnt lgkmcnt(1)
	v_mov_b32_e32 v6, v12
	v_mov_b32_e32 v7, v14
	v_pk_mul_f32 v[6:7], v[6:7], v[0:1] op_sel_hi:[1,0]
	v_mov_b32_e32 v14, v13
	v_pk_mul_f32 v[12:13], v[14:15], v[0:1] op_sel_hi:[1,0]
	v_and_b32_sdwa v14, v7, v242 dst_sel:DWORD dst_unused:UNUSED_PAD src0_sel:WORD_1 src1_sel:DWORD
	v_and_b32_sdwa v15, v6, v242 dst_sel:DWORD dst_unused:UNUSED_PAD src0_sel:WORD_1 src1_sel:DWORD
	v_add3_u32 v6, v6, v15, s71
	v_add3_u32 v7, v7, v14, s71
	v_and_b32_sdwa v14, v13, v242 dst_sel:DWORD dst_unused:UNUSED_PAD src0_sel:WORD_1 src1_sel:DWORD
	v_and_b32_sdwa v15, v12, v242 dst_sel:DWORD dst_unused:UNUSED_PAD src0_sel:WORD_1 src1_sel:DWORD
	v_add3_u32 v13, v13, v14, s71
	v_add3_u32 v12, v12, v15, s71
	v_and_b32_e32 v13, 0xffff0000, v13
	v_and_b32_e32 v12, 0xffff0000, v12
	v_or_b32_sdwa v89, v13, v7 dst_sel:DWORD dst_unused:UNUSED_PAD src0_sel:DWORD src1_sel:WORD_1
	v_or_b32_sdwa v88, v12, v6 dst_sel:DWORD dst_unused:UNUSED_PAD src0_sel:DWORD src1_sel:WORD_1
	s_waitcnt lgkmcnt(0)
	v_mov_b32_e32 v6, v84
	v_mov_b32_e32 v7, v86
	v_pk_mul_f32 v[6:7], v[0:1], v[6:7] op_sel_hi:[0,1]
	v_mov_b32_e32 v86, v85
	v_pk_mul_f32 v[12:13], v[0:1], v[86:87] op_sel_hi:[0,1]
	v_and_b32_sdwa v0, v7, v242 dst_sel:DWORD dst_unused:UNUSED_PAD src0_sel:WORD_1 src1_sel:DWORD
	v_and_b32_sdwa v14, v6, v242 dst_sel:DWORD dst_unused:UNUSED_PAD src0_sel:WORD_1 src1_sel:DWORD
	v_add3_u32 v0, v7, v0, s71
	v_and_b32_sdwa v7, v13, v242 dst_sel:DWORD dst_unused:UNUSED_PAD src0_sel:WORD_1 src1_sel:DWORD
	v_add3_u32 v6, v6, v14, s71
	v_and_b32_sdwa v14, v12, v242 dst_sel:DWORD dst_unused:UNUSED_PAD src0_sel:WORD_1 src1_sel:DWORD
	v_add3_u32 v7, v13, v7, s71
	v_add_u32_e32 v13, 0x100, v4
	v_add3_u32 v12, v12, v14, s71
	v_ashrrev_i32_e32 v14, 4, v13
	v_lshlrev_b32_e32 v13, 2, v14
	v_sub_u32_e32 v13, v104, v13
	ds_read_b32 v13, v13 offset:508
	v_and_b32_e32 v12, 0xffff0000, v12
	v_and_b32_e32 v7, 0xffff0000, v7
	v_or_b32_sdwa v90, v12, v6 dst_sel:DWORD dst_unused:UNUSED_PAD src0_sel:DWORD src1_sel:WORD_1
	v_sub_u32_e32 v6, 63, v14
	v_or_b32_sdwa v91, v7, v0 dst_sel:DWORD dst_unused:UNUSED_PAD src0_sel:DWORD src1_sel:WORD_1
	v_mad_u64_u32 v[6:7], s[20:21], v6, s84, v[10:11]
	ds_read_b128 v[84:87], v6
	s_waitcnt lgkmcnt(1)
	v_mul_f32_e32 v0, 0x3fb8aa3b, v13
	v_exp_f32_e32 v0, v0
	global_store_dwordx4 v[94:95], v[88:91], off
	v_ashrrev_i32_e32 v15, 31, v14
	ds_read_b128 v[88:91], v6 offset:16
	s_waitcnt lgkmcnt(1)
	v_mov_b32_e32 v6, v84
	v_mov_b32_e32 v7, v86
	v_and_b32_e32 v12, 15, v14
	v_lshrrev_b32_e32 v13, 4, v14
	v_lshlrev_b32_e32 v12, 4, v12
	v_lshl_add_u32 v12, v13, 12, v12
	v_mov_b32_e32 v13, 0
	v_pk_mul_f32 v[6:7], v[6:7], v[0:1] op_sel_hi:[1,0]
	v_mov_b32_e32 v86, v85
	v_lshl_add_u64 v[94:95], v[92:93], 0, v[12:13]
	v_pk_mul_f32 v[12:13], v[86:87], v[0:1] op_sel_hi:[1,0]
	v_and_b32_sdwa v15, v7, v242 dst_sel:DWORD dst_unused:UNUSED_PAD src0_sel:WORD_1 src1_sel:DWORD
	v_and_b32_sdwa v17, v6, v242 dst_sel:DWORD dst_unused:UNUSED_PAD src0_sel:WORD_1 src1_sel:DWORD
	v_add3_u32 v6, v6, v17, s71
	v_add3_u32 v7, v7, v15, s71
	v_and_b32_sdwa v15, v13, v242 dst_sel:DWORD dst_unused:UNUSED_PAD src0_sel:WORD_1 src1_sel:DWORD
	v_and_b32_sdwa v17, v12, v242 dst_sel:DWORD dst_unused:UNUSED_PAD src0_sel:WORD_1 src1_sel:DWORD
	v_add3_u32 v13, v13, v15, s71
	v_add3_u32 v12, v12, v17, s71
	v_and_b32_e32 v13, 0xffff0000, v13
	v_and_b32_e32 v12, 0xffff0000, v12
	v_or_b32_sdwa v85, v13, v7 dst_sel:DWORD dst_unused:UNUSED_PAD src0_sel:DWORD src1_sel:WORD_1
	v_or_b32_sdwa v84, v12, v6 dst_sel:DWORD dst_unused:UNUSED_PAD src0_sel:DWORD src1_sel:WORD_1
	s_waitcnt lgkmcnt(0)
	v_mov_b32_e32 v6, v88
	v_mov_b32_e32 v7, v90
	v_pk_mul_f32 v[6:7], v[0:1], v[6:7] op_sel_hi:[0,1]
	v_mov_b32_e32 v90, v89
	v_pk_mul_f32 v[12:13], v[0:1], v[90:91] op_sel_hi:[0,1]
	v_and_b32_sdwa v15, v6, v242 dst_sel:DWORD dst_unused:UNUSED_PAD src0_sel:WORD_1 src1_sel:DWORD
	v_and_b32_sdwa v0, v7, v242 dst_sel:DWORD dst_unused:UNUSED_PAD src0_sel:WORD_1 src1_sel:DWORD
	v_add3_u32 v6, v6, v15, s71
	v_and_b32_sdwa v15, v12, v242 dst_sel:DWORD dst_unused:UNUSED_PAD src0_sel:WORD_1 src1_sel:DWORD
	v_add3_u32 v0, v7, v0, s71
	v_and_b32_sdwa v7, v13, v242 dst_sel:DWORD dst_unused:UNUSED_PAD src0_sel:WORD_1 src1_sel:DWORD
	v_add3_u32 v12, v12, v15, s71
	v_add3_u32 v7, v13, v7, s71
	v_and_b32_e32 v13, 0xffff0000, v12
	v_add_u32_e32 v12, 0x200, v4
	v_ashrrev_i32_e32 v12, 4, v12
	v_lshlrev_b32_e32 v15, 2, v12
	v_sub_u32_e32 v15, v104, v15
	ds_read_b32 v15, v15 offset:508
	v_and_b32_e32 v7, 0xffff0000, v7
	v_or_b32_sdwa v86, v13, v6 dst_sel:DWORD dst_unused:UNUSED_PAD src0_sel:DWORD src1_sel:WORD_1
	v_sub_u32_e32 v6, 63, v12
	v_or_b32_sdwa v87, v7, v0 dst_sel:DWORD dst_unused:UNUSED_PAD src0_sel:DWORD src1_sel:WORD_1
	v_mad_u64_u32 v[6:7], s[20:21], v6, s84, v[10:11]
	global_store_dwordx4 v[94:95], v[84:87], off
	ds_read_b128 v[84:87], v6
	s_waitcnt lgkmcnt(1)
; DI unsigned pk2(float lo, float hi) { return f2bf(lo) | (f2bf(hi) << 16); }
; DI uint4 pack8(const float* f) { uint4 o; o.x = pk2(f[0], f[1]); o.y = pk2(f[2], f[3]); o.z = pk2(f[4], f[5]); o.w = pk2(f[6], f[7]); return o; }
; template <int D> DI void dn_out(float (&x)[64], lf_t Kl, lf_t Ql, lf_t Gn, bf16_t* DW, bf16_t* DQE, bf16_t* DKT, bf16_t* DUT, float* DEG, int item, int t) {
;     ...
;             for (int i = 0; i < 4; ++i) { const int idx = t + 256 * i, pi = idx >> 4, seg = idx & 15, n = D ? 63 - pi : pi; const float e = __expf(Gd[n]);
;                 const float4 a0 = *(const float4*)(Ql + n * 132 + seg * 8), a1 = *(const float4*)(Ql + n * 132 + seg * 8 + 4);
;                 uint4 o; o.x = pk2(a0.x * e, a0.y * e); o.y = pk2(a0.z * e, a0.w * e); o.z = pk2(a1.x * e, a1.y * e); o.w = pk2(a1.z * e, a1.w * e);
;                 *(uint4*)(DQE + (((size_t)D * 1152 + item) * 64 + pi) * 128 + seg * 8) = o; }
; #pragma unroll
;             for (int i = 0; i < 4; ++i) { const int idx = t + 256 * i, dk = idx & 127, pg = idx >> 7; float v[8];
; #pragma unroll
;                 for (int e = 0; e < 8; ++e) { const int pi = 8 * pg + e, n = D ? 63 - pi : pi; v[e] = Kl[n * 132 + dk] * __expf(glast - Gd[n]); }
;                 *(uint4*)(DKT + (((size_t)D * 1152 + item) * 128 + dk) * 64 + 8 * pg) = pack8(v); }
	v_mul_f32_e32 v0, 0x3fb8aa3b, v15
	v_exp_f32_e32 v0, v0
	v_ashrrev_i32_e32 v13, 31, v12
	v_and_b32_e32 v88, 15, v12
	v_lshrrev_b32_e32 v89, 4, v12
	v_lshlrev_b32_e32 v88, 4, v88
	v_lshl_add_u32 v88, v89, 12, v88
	v_mov_b32_e32 v89, 0
	v_lshl_add_u64 v[94:95], v[92:93], 0, v[88:89]
	ds_read_b128 v[88:91], v6 offset:16
	s_waitcnt lgkmcnt(1)
	v_mov_b32_e32 v6, v84
	v_mov_b32_e32 v7, v86
	v_pk_mul_f32 v[6:7], v[6:7], v[0:1] op_sel_hi:[1,0]
	v_mov_b32_e32 v86, v85
	v_pk_mul_f32 v[84:85], v[86:87], v[0:1] op_sel_hi:[1,0]
	v_and_b32_sdwa v13, v7, v242 dst_sel:DWORD dst_unused:UNUSED_PAD src0_sel:WORD_1 src1_sel:DWORD
	v_and_b32_sdwa v15, v6, v242 dst_sel:DWORD dst_unused:UNUSED_PAD src0_sel:WORD_1 src1_sel:DWORD
	v_add3_u32 v6, v6, v15, s71
	v_add3_u32 v7, v7, v13, s71
	v_and_b32_sdwa v13, v85, v242 dst_sel:DWORD dst_unused:UNUSED_PAD src0_sel:WORD_1 src1_sel:DWORD
	v_and_b32_sdwa v15, v84, v242 dst_sel:DWORD dst_unused:UNUSED_PAD src0_sel:WORD_1 src1_sel:DWORD
	v_add3_u32 v13, v85, v13, s71
	v_add3_u32 v15, v84, v15, s71
	v_and_b32_e32 v13, 0xffff0000, v13
	v_and_b32_e32 v15, 0xffff0000, v15
	v_or_b32_sdwa v85, v13, v7 dst_sel:DWORD dst_unused:UNUSED_PAD src0_sel:DWORD src1_sel:WORD_1
	v_or_b32_sdwa v84, v15, v6 dst_sel:DWORD dst_unused:UNUSED_PAD src0_sel:DWORD src1_sel:WORD_1
	s_waitcnt lgkmcnt(0)
	v_mov_b32_e32 v6, v88
	v_mov_b32_e32 v7, v90
	v_pk_mul_f32 v[6:7], v[0:1], v[6:7] op_sel_hi:[0,1]
	v_mov_b32_e32 v90, v89
	v_pk_mul_f32 v[86:87], v[0:1], v[90:91] op_sel_hi:[0,1]
	v_and_b32_sdwa v13, v6, v242 dst_sel:DWORD dst_unused:UNUSED_PAD src0_sel:WORD_1 src1_sel:DWORD
	v_add3_u32 v13, v6, v13, s71
	v_and_b32_sdwa v6, v87, v242 dst_sel:DWORD dst_unused:UNUSED_PAD src0_sel:WORD_1 src1_sel:DWORD
	v_add3_u32 v6, v87, v6, s71
	v_and_b32_e32 v15, 0xffff0000, v6
	v_add_u32_e32 v6, 0x300, v4
	v_ashrrev_i32_e32 v6, 4, v6
	v_and_b32_sdwa v0, v7, v242 dst_sel:DWORD dst_unused:UNUSED_PAD src0_sel:WORD_1 src1_sel:DWORD
	v_lshlrev_b32_e32 v17, 2, v6
	v_add3_u32 v0, v7, v0, s71
	v_and_b32_sdwa v7, v86, v242 dst_sel:DWORD dst_unused:UNUSED_PAD src0_sel:WORD_1 src1_sel:DWORD
	v_sub_u32_e32 v17, v104, v17
	v_add3_u32 v7, v86, v7, s71
	ds_read_b32 v17, v17 offset:508
	v_and_b32_e32 v7, 0xffff0000, v7
	v_or_b32_sdwa v86, v7, v13 dst_sel:DWORD dst_unused:UNUSED_PAD src0_sel:DWORD src1_sel:WORD_1
	v_sub_u32_e32 v7, 63, v6
	v_or_b32_sdwa v87, v15, v0 dst_sel:DWORD dst_unused:UNUSED_PAD src0_sel:DWORD src1_sel:WORD_1
	v_mad_u64_u32 v[88:89], s[20:21], v7, s84, v[10:11]
	global_store_dwordx4 v[94:95], v[84:87], off
	ds_read_b128 v[84:87], v88
	s_waitcnt lgkmcnt(1)
	v_mul_f32_e32 v0, 0x3fb8aa3b, v17
	v_ashrrev_i32_e32 v7, 31, v6
	v_exp_f32_e32 v0, v0
	v_and_b32_e32 v90, 15, v6
	v_lshrrev_b32_e32 v91, 4, v6
	v_lshlrev_b32_e32 v90, 4, v90
	v_lshl_add_u32 v90, v91, 12, v90
	v_mov_b32_e32 v91, 0
	v_lshl_add_u64 v[92:93], v[92:93], 0, v[90:91]
	ds_read_b128 v[88:91], v88 offset:16
	s_waitcnt lgkmcnt(1)
	v_mov_b32_e32 v95, v86
	v_mov_b32_e32 v86, v85
	v_mov_b32_e32 v94, v84
	v_pk_mul_f32 v[84:85], v[86:87], v[0:1] op_sel_hi:[1,0]
	v_pk_mul_f32 v[94:95], v[94:95], v[0:1] op_sel_hi:[1,0]
	v_and_b32_sdwa v13, v85, v242 dst_sel:DWORD dst_unused:UNUSED_PAD src0_sel:WORD_1 src1_sel:DWORD
	v_and_b32_sdwa v15, v84, v242 dst_sel:DWORD dst_unused:UNUSED_PAD src0_sel:WORD_1 src1_sel:DWORD
	v_and_b32_sdwa v7, v95, v242 dst_sel:DWORD dst_unused:UNUSED_PAD src0_sel:WORD_1 src1_sel:DWORD
	v_and_b32_sdwa v10, v94, v242 dst_sel:DWORD dst_unused:UNUSED_PAD src0_sel:WORD_1 src1_sel:DWORD
	v_add3_u32 v13, v85, v13, s71
	v_add3_u32 v15, v84, v15, s71
	s_waitcnt lgkmcnt(0)
	v_mov_b32_e32 v87, v90
	v_mov_b32_e32 v90, v89
	v_add3_u32 v10, v94, v10, s71
	v_add3_u32 v7, v95, v7, s71
	v_and_b32_e32 v13, 0xffff0000, v13
	v_and_b32_e32 v15, 0xffff0000, v15
	v_mov_b32_e32 v86, v88
	v_pk_mul_f32 v[88:89], v[0:1], v[90:91] op_sel_hi:[0,1]
	v_or_b32_sdwa v85, v13, v7 dst_sel:DWORD dst_unused:UNUSED_PAD src0_sel:DWORD src1_sel:WORD_1
	v_or_b32_sdwa v84, v15, v10 dst_sel:DWORD dst_unused:UNUSED_PAD src0_sel:DWORD src1_sel:WORD_1
	v_pk_mul_f32 v[86:87], v[0:1], v[86:87] op_sel_hi:[0,1]
	v_and_b32_sdwa v10, v89, v242 dst_sel:DWORD dst_unused:UNUSED_PAD src0_sel:WORD_1 src1_sel:DWORD
	v_and_b32_sdwa v13, v88, v242 dst_sel:DWORD dst_unused:UNUSED_PAD src0_sel:WORD_1 src1_sel:DWORD
	v_and_b32_sdwa v0, v87, v242 dst_sel:DWORD dst_unused:UNUSED_PAD src0_sel:WORD_1 src1_sel:DWORD
	v_and_b32_sdwa v7, v86, v242 dst_sel:DWORD dst_unused:UNUSED_PAD src0_sel:WORD_1 src1_sel:DWORD
	v_add3_u32 v10, v89, v10, s71
	v_add3_u32 v13, v88, v13, s71
	v_add3_u32 v7, v86, v7, s71
	v_add3_u32 v0, v87, v0, s71
	v_and_b32_e32 v10, 0xffff0000, v10
	v_and_b32_e32 v13, 0xffff0000, v13
	v_or_b32_sdwa v87, v10, v0 dst_sel:DWORD dst_unused:UNUSED_PAD src0_sel:DWORD src1_sel:WORD_1
	v_or_b32_sdwa v86, v13, v7 dst_sel:DWORD dst_unused:UNUSED_PAD src0_sel:DWORD src1_sel:WORD_1
	v_and_b32_e32 v0, 0x7f, v4
	global_store_dwordx4 v[92:93], v[84:87], off
	v_lshl_add_u32 v10, v0, 2, v100
	v_lshl_add_u64 v[8:9], s[48:49], 0, v[8:9]
	s_nop 0
	v_and_b32_e32 v84, 15, v0
	v_lshrrev_b32_e32 v0, 4, v0
	v_lshlrev_b32_e32 v0, 11, v0
	v_lshl_add_u32 v0, v84, 4, v0
	v_and_b32_e32 v84, -8, v16
	v_lshl_add_u64 v[8:9], v[8:9], 0, v[0:1]
	v_lshlrev_b32_e32 v0, 2, v84
	v_sub_u32_e32 v0, v104, v0
	ds_read_b32 v5, v104 offset:256
	ds_read_b32 v0, v0 offset:508
	v_sub_u32_e32 v7, 63, v84
	v_mad_u64_u32 v[86:87], s[20:21], v7, s84, v[10:11]
	ds_read_b32 v86, v86
	s_waitcnt lgkmcnt(1)
	v_sub_f32_e32 v0, v5, v0
	v_mul_f32_e32 v0, 0x3fb8aa3b, v0
	v_exp_f32_e32 v88, v0
	v_or_b32_e32 v0, 2, v84
	v_lshlrev_b32_e32 v7, 2, v0
	v_sub_u32_e32 v7, v104, v7
	ds_read2_b32 v[90:91], v7 offset0:127 offset1:128
	v_sub_u32_e32 v7, 62, v84
	v_mad_u64_u32 v[92:93], s[20:21], v7, s84, v[10:11]
	v_sub_u32_e32 v0, 63, v0
	s_waitcnt lgkmcnt(0)
; DI uint4 pack8(const float* f) { uint4 o; o.x = pk2(f[0], f[1]); o.y = pk2(f[2], f[3]); o.z = pk2(f[4], f[5]); o.w = pk2(f[6], f[7]); return o; }
; template <int D> DI void dn_out(float (&x)[64], lf_t Kl, lf_t Ql, lf_t Gn, bf16_t* DW, bf16_t* DQE, bf16_t* DKT, bf16_t* DUT, float* DEG, int item, int t) {
;     ...
;             for (int i = 0; i < 4; ++i) { const int idx = t + 256 * i, dk = idx & 127, pg = idx >> 7; float v[8];
; #pragma unroll
;                 for (int e = 0; e < 8; ++e) { const int pi = 8 * pg + e, n = D ? 63 - pi : pi; v[e] = Kl[n * 132 + dk] * __expf(glast - Gd[n]); }
;                 *(uint4*)(DKT + (((size_t)D * 1152 + item) * 128 + dk) * 64 + 8 * pg) = pack8(v); }
	v_sub_f32_e32 v7, v5, v91
	v_mul_f32_e32 v7, 0x3fb8aa3b, v7
	v_exp_f32_e32 v94, v7
	v_or_b32_e32 v7, 4, v84
	v_lshlrev_b32_e32 v13, 2, v7
	v_sub_u32_e32 v13, v104, v13
	v_mad_u64_u32 v[96:97], s[20:21], v0, s84, v[10:11]
	v_sub_f32_e32 v0, v5, v90
	ds_read2_b32 v[90:91], v13 offset0:127 offset1:128
	v_mul_f32_e32 v0, 0x3fb8aa3b, v0
	v_exp_f32_e32 v89, v0
	v_or_b32_e32 v0, 3, v84
	v_sub_u32_e32 v0, 63, v0
	v_mad_u64_u32 v[98:99], s[20:21], v0, s84, v[10:11]
	s_waitcnt lgkmcnt(0)
	v_sub_f32_e32 v0, v5, v91
	v_mul_f32_e32 v0, 0x3fb8aa3b, v0
	v_exp_f32_e32 v95, v0
	v_sub_u32_e32 v0, 63, v7
	v_or_b32_e32 v7, 6, v84
	v_lshlrev_b32_e32 v13, 2, v7
	v_sub_u32_e32 v13, v104, v13
	ds_read_b32 v92, v92
	ds_read_b32 v87, v96
	ds_read_b32 v93, v98
	ds_read2_b32 v[98:99], v13 offset0:127 offset1:128
	v_mad_u64_u32 v[96:97], s[20:21], v0, s84, v[10:11]
	v_sub_f32_e32 v0, v5, v90
	v_mul_f32_e32 v0, 0x3fb8aa3b, v0
	v_exp_f32_e32 v90, v0
	v_or_b32_e32 v0, 5, v84
	v_sub_u32_e32 v0, 63, v0
	v_mad_u64_u32 v[126:127], s[20:21], v0, s84, v[10:11]
	s_waitcnt lgkmcnt(0)
	v_sub_f32_e32 v0, v5, v99
	v_mul_f32_e32 v0, 0x3fb8aa3b, v0
	v_exp_f32_e32 v128, v0
	v_sub_u32_e32 v0, 63, v7
	v_mad_u64_u32 v[130:131], s[20:21], v0, s84, v[10:11]
	v_sub_f32_e32 v0, v5, v98
	v_mul_f32_e32 v0, 0x3fb8aa3b, v0
	v_exp_f32_e32 v91, v0
	v_or_b32_e32 v0, 7, v16
	v_sub_u32_e32 v7, 63, v0
	v_lshlrev_b32_e32 v0, 2, v0
	v_sub_u32_e32 v0, v104, v0
	ds_read_b32 v96, v96
	ds_read_b32 v126, v126
	ds_read_b32 v0, v0 offset:508
	v_mad_u64_u32 v[16:17], s[20:21], v7, s84, v[10:11]
	ds_read_b32 v97, v130
	ds_read_b32 v127, v16
	v_ashrrev_i32_e32 v85, 31, v84
	s_waitcnt lgkmcnt(2)
	v_sub_f32_e32 v0, v5, v0
	v_mul_f32_e32 v0, 0x3fb8aa3b, v0
	v_exp_f32_e32 v129, v0
	v_lshlrev_b32_e32 v16, 5, v84
	v_mov_b32_e32 v17, 0
	v_lshl_add_u64 v[16:17], v[8:9], 0, v[16:17]
	v_pk_mul_f32 v[84:85], v[86:87], v[88:89]
	v_pk_mul_f32 v[86:87], v[92:93], v[94:95]
	v_and_b32_sdwa v0, v85, v242 dst_sel:DWORD dst_unused:UNUSED_PAD src0_sel:WORD_1 src1_sel:DWORD
	v_and_b32_sdwa v13, v87, v242 dst_sel:DWORD dst_unused:UNUSED_PAD src0_sel:WORD_1 src1_sel:DWORD
	v_and_b32_sdwa v15, v86, v242 dst_sel:DWORD dst_unused:UNUSED_PAD src0_sel:WORD_1 src1_sel:DWORD
	v_and_b32_sdwa v7, v84, v242 dst_sel:DWORD dst_unused:UNUSED_PAD src0_sel:WORD_1 src1_sel:DWORD
	v_add3_u32 v13, v87, v13, s71
	v_add3_u32 v15, v86, v15, s71
	v_add3_u32 v7, v84, v7, s71
	v_add3_u32 v0, v85, v0, s71
	v_and_b32_e32 v13, 0xffff0000, v13
	v_and_b32_e32 v15, 0xffff0000, v15
	s_waitcnt lgkmcnt(0)
	v_pk_mul_f32 v[88:89], v[126:127], v[128:129]
	v_or_b32_sdwa v85, v13, v0 dst_sel:DWORD dst_unused:UNUSED_PAD src0_sel:DWORD src1_sel:WORD_1
	v_or_b32_sdwa v84, v15, v7 dst_sel:DWORD dst_unused:UNUSED_PAD src0_sel:DWORD src1_sel:WORD_1
	v_pk_mul_f32 v[86:87], v[96:97], v[90:91]
	v_and_b32_sdwa v13, v89, v242 dst_sel:DWORD dst_unused:UNUSED_PAD src0_sel:WORD_1 src1_sel:DWORD
	v_and_b32_sdwa v15, v88, v242 dst_sel:DWORD dst_unused:UNUSED_PAD src0_sel:WORD_1 src1_sel:DWORD
	v_and_b32_sdwa v0, v87, v242 dst_sel:DWORD dst_unused:UNUSED_PAD src0_sel:WORD_1 src1_sel:DWORD
	v_and_b32_sdwa v7, v86, v242 dst_sel:DWORD dst_unused:UNUSED_PAD src0_sel:WORD_1 src1_sel:DWORD
	v_add3_u32 v13, v89, v13, s71
	v_add3_u32 v15, v88, v15, s71
	v_add3_u32 v7, v86, v7, s71
	v_add3_u32 v0, v87, v0, s71
	v_and_b32_e32 v13, 0xffff0000, v13
	v_and_b32_e32 v15, 0xffff0000, v15
	v_or_b32_sdwa v87, v13, v0 dst_sel:DWORD dst_unused:UNUSED_PAD src0_sel:DWORD src1_sel:WORD_1
	v_or_b32_sdwa v86, v15, v7 dst_sel:DWORD dst_unused:UNUSED_PAD src0_sel:DWORD src1_sel:WORD_1
	global_store_dwordx4 v[16:17], v[84:87], off
	v_and_b32_e32 v16, -8, v14
	v_lshlrev_b32_e32 v0, 2, v16
	v_sub_u32_e32 v0, v104, v0
	ds_read_b32 v0, v0 offset:508
	v_sub_u32_e32 v7, 63, v16
	v_mad_u64_u32 v[84:85], s[20:21], v7, s84, v[10:11]
	ds_read_b32 v84, v84
	s_waitcnt lgkmcnt(1)
	v_sub_f32_e32 v0, v5, v0
	v_mul_f32_e32 v0, 0x3fb8aa3b, v0
	v_exp_f32_e32 v86, v0
	v_or_b32_e32 v0, 2, v16
	v_lshlrev_b32_e32 v7, 2, v0
	v_sub_u32_e32 v7, v104, v7
	ds_read2_b32 v[88:89], v7 offset0:127 offset1:128
	v_sub_u32_e32 v7, 62, v16
	v_mad_u64_u32 v[90:91], s[20:21], v7, s84, v[10:11]
	v_sub_u32_e32 v0, 63, v0
	s_waitcnt lgkmcnt(0)
	v_sub_f32_e32 v7, v5, v89
	v_mul_f32_e32 v7, 0x3fb8aa3b, v7
	v_exp_f32_e32 v92, v7
	v_or_b32_e32 v7, 4, v16
	v_lshlrev_b32_e32 v13, 2, v7
	v_sub_u32_e32 v13, v104, v13
	v_mad_u64_u32 v[94:95], s[20:21], v0, s84, v[10:11]
	v_sub_f32_e32 v0, v5, v88
	ds_read2_b32 v[88:89], v13 offset0:127 offset1:128
	v_mul_f32_e32 v0, 0x3fb8aa3b, v0
	v_exp_f32_e32 v87, v0
	v_or_b32_e32 v0, 3, v16
	v_sub_u32_e32 v0, 63, v0
	v_mad_u64_u32 v[96:97], s[20:21], v0, s84, v[10:11]
	s_waitcnt lgkmcnt(0)
	v_sub_f32_e32 v0, v5, v89
	v_mul_f32_e32 v0, 0x3fb8aa3b, v0
	v_exp_f32_e32 v93, v0
	v_sub_u32_e32 v0, 63, v7
	v_or_b32_e32 v7, 6, v16
	v_lshlrev_b32_e32 v13, 2, v7
	v_sub_u32_e32 v13, v104, v13
	ds_read_b32 v90, v90
	ds_read_b32 v85, v94
	ds_read_b32 v91, v96
	ds_read2_b32 v[96:97], v13 offset0:127 offset1:128
	v_mad_u64_u32 v[94:95], s[20:21], v0, s84, v[10:11]
	v_sub_f32_e32 v0, v5, v88
	v_mul_f32_e32 v0, 0x3fb8aa3b, v0
	v_exp_f32_e32 v88, v0
	v_or_b32_e32 v0, 5, v16
	v_sub_u32_e32 v0, 63, v0
	v_mad_u64_u32 v[98:99], s[20:21], v0, s84, v[10:11]
	s_waitcnt lgkmcnt(0)
	v_sub_f32_e32 v0, v5, v97
	v_mul_f32_e32 v0, 0x3fb8aa3b, v0
	v_exp_f32_e32 v126, v0
	v_sub_u32_e32 v0, 63, v7
	v_mad_u64_u32 v[128:129], s[20:21], v0, s84, v[10:11]
	v_sub_f32_e32 v0, v5, v96
	v_mul_f32_e32 v0, 0x3fb8aa3b, v0
	v_exp_f32_e32 v89, v0
	v_or_b32_e32 v0, 7, v14
	v_sub_u32_e32 v7, 63, v0
	v_lshlrev_b32_e32 v0, 2, v0
	v_sub_u32_e32 v0, v104, v0
	ds_read_b32 v94, v94
	ds_read_b32 v98, v98
	ds_read_b32 v0, v0 offset:508
	v_mad_u64_u32 v[14:15], s[20:21], v7, s84, v[10:11]
	ds_read_b32 v95, v128
	ds_read_b32 v99, v14
	v_ashrrev_i32_e32 v17, 31, v16
	s_waitcnt lgkmcnt(2)
; DI uint4 pack8(const float* f) { uint4 o; o.x = pk2(f[0], f[1]); o.y = pk2(f[2], f[3]); o.z = pk2(f[4], f[5]); o.w = pk2(f[6], f[7]); return o; }
; template <int D> DI void dn_out(float (&x)[64], lf_t Kl, lf_t Ql, lf_t Gn, bf16_t* DW, bf16_t* DQE, bf16_t* DKT, bf16_t* DUT, float* DEG, int item, int t) {
;     ...
;             for (int i = 0; i < 4; ++i) { const int idx = t + 256 * i, dk = idx & 127, pg = idx >> 7; float v[8];
; #pragma unroll
;                 for (int e = 0; e < 8; ++e) { const int pi = 8 * pg + e, n = D ? 63 - pi : pi; v[e] = Kl[n * 132 + dk] * __expf(glast - Gd[n]); }
;                 *(uint4*)(DKT + (((size_t)D * 1152 + item) * 128 + dk) * 64 + 8 * pg) = pack8(v); }
	v_sub_f32_e32 v0, v5, v0
	v_mul_f32_e32 v0, 0x3fb8aa3b, v0
	v_pk_mul_f32 v[14:15], v[84:85], v[86:87]
	v_exp_f32_e32 v127, v0
	v_lshlrev_b32_e32 v96, 5, v16
	v_mov_b32_e32 v97, 0
	v_lshl_add_u64 v[96:97], v[8:9], 0, v[96:97]
	v_pk_mul_f32 v[16:17], v[90:91], v[92:93]
	v_and_b32_sdwa v7, v14, v242 dst_sel:DWORD dst_unused:UNUSED_PAD src0_sel:WORD_1 src1_sel:DWORD
	v_add3_u32 v7, v14, v7, s71
	v_and_b32_sdwa v14, v16, v242 dst_sel:DWORD dst_unused:UNUSED_PAD src0_sel:WORD_1 src1_sel:DWORD
	v_and_b32_sdwa v13, v17, v242 dst_sel:DWORD dst_unused:UNUSED_PAD src0_sel:WORD_1 src1_sel:DWORD
	v_add3_u32 v14, v16, v14, s71
	v_and_b32_sdwa v0, v15, v242 dst_sel:DWORD dst_unused:UNUSED_PAD src0_sel:WORD_1 src1_sel:DWORD
	v_add3_u32 v13, v17, v13, s71
	v_and_b32_e32 v14, 0xffff0000, v14
	s_waitcnt lgkmcnt(1)
	v_pk_mul_f32 v[16:17], v[94:95], v[88:89]
	v_add3_u32 v0, v15, v0, s71
	v_and_b32_e32 v13, 0xffff0000, v13
	v_or_b32_sdwa v14, v14, v7 dst_sel:DWORD dst_unused:UNUSED_PAD src0_sel:DWORD src1_sel:WORD_1
	s_waitcnt lgkmcnt(0)
	v_pk_mul_f32 v[84:85], v[98:99], v[126:127]
	v_and_b32_sdwa v7, v16, v242 dst_sel:DWORD dst_unused:UNUSED_PAD src0_sel:WORD_1 src1_sel:DWORD
	v_or_b32_sdwa v15, v13, v0 dst_sel:DWORD dst_unused:UNUSED_PAD src0_sel:DWORD src1_sel:WORD_1
	v_add3_u32 v7, v16, v7, s71
	v_and_b32_sdwa v13, v85, v242 dst_sel:DWORD dst_unused:UNUSED_PAD src0_sel:WORD_1 src1_sel:DWORD
	v_and_b32_sdwa v16, v84, v242 dst_sel:DWORD dst_unused:UNUSED_PAD src0_sel:WORD_1 src1_sel:DWORD
	v_and_b32_sdwa v0, v17, v242 dst_sel:DWORD dst_unused:UNUSED_PAD src0_sel:WORD_1 src1_sel:DWORD
	v_add3_u32 v13, v85, v13, s71
	v_add3_u32 v16, v84, v16, s71
	v_add3_u32 v0, v17, v0, s71
	v_and_b32_e32 v13, 0xffff0000, v13
	v_and_b32_e32 v16, 0xffff0000, v16
	v_or_b32_sdwa v17, v13, v0 dst_sel:DWORD dst_unused:UNUSED_PAD src0_sel:DWORD src1_sel:WORD_1
	v_or_b32_sdwa v16, v16, v7 dst_sel:DWORD dst_unused:UNUSED_PAD src0_sel:DWORD src1_sel:WORD_1
	global_store_dwordx4 v[96:97], v[14:17], off
	v_cmp_eq_u32_e32 vcc, 0, v4
	s_nop 0
	v_and_b32_e32 v14, -8, v12
	v_lshlrev_b32_e32 v0, 2, v14
	v_sub_u32_e32 v0, v104, v0
	ds_read_b32 v0, v0 offset:508
	v_sub_u32_e32 v7, 63, v14
	v_mad_u64_u32 v[16:17], s[20:21], v7, s84, v[10:11]
	ds_read_b32 v16, v16
	s_waitcnt lgkmcnt(1)
	v_sub_f32_e32 v0, v5, v0
	v_mul_f32_e32 v0, 0x3fb8aa3b, v0
	v_exp_f32_e32 v84, v0
	v_or_b32_e32 v0, 2, v14
	v_lshlrev_b32_e32 v7, 2, v0
	v_sub_u32_e32 v7, v104, v7
	ds_read2_b32 v[86:87], v7 offset0:127 offset1:128
	v_sub_u32_e32 v7, 62, v14
	v_mad_u64_u32 v[88:89], s[20:21], v7, s84, v[10:11]
	v_sub_u32_e32 v0, 63, v0
	s_waitcnt lgkmcnt(0)
	v_sub_f32_e32 v7, v5, v87
	v_mul_f32_e32 v7, 0x3fb8aa3b, v7
	v_exp_f32_e32 v90, v7
	v_or_b32_e32 v7, 4, v14
	v_lshlrev_b32_e32 v13, 2, v7
	v_sub_u32_e32 v13, v104, v13
	v_mad_u64_u32 v[92:93], s[20:21], v0, s84, v[10:11]
	v_sub_f32_e32 v0, v5, v86
	ds_read2_b32 v[86:87], v13 offset0:127 offset1:128
	v_mul_f32_e32 v0, 0x3fb8aa3b, v0
	v_exp_f32_e32 v85, v0
	v_or_b32_e32 v0, 3, v14
	v_sub_u32_e32 v0, 63, v0
	v_mad_u64_u32 v[94:95], s[20:21], v0, s84, v[10:11]
	s_waitcnt lgkmcnt(0)
	v_sub_f32_e32 v0, v5, v87
	v_mul_f32_e32 v0, 0x3fb8aa3b, v0
	v_exp_f32_e32 v91, v0
	v_sub_u32_e32 v0, 63, v7
	v_or_b32_e32 v7, 6, v14
	v_lshlrev_b32_e32 v13, 2, v7
	v_sub_u32_e32 v13, v104, v13
	ds_read_b32 v88, v88
	ds_read_b32 v17, v92
	ds_read_b32 v89, v94
	ds_read2_b32 v[94:95], v13 offset0:127 offset1:128
	v_mad_u64_u32 v[92:93], s[20:21], v0, s84, v[10:11]
	v_sub_f32_e32 v0, v5, v86
	v_mul_f32_e32 v0, 0x3fb8aa3b, v0
	v_exp_f32_e32 v86, v0
	v_or_b32_e32 v0, 5, v14
	v_sub_u32_e32 v0, 63, v0
	v_mad_u64_u32 v[96:97], s[20:21], v0, s84, v[10:11]
	s_waitcnt lgkmcnt(0)
	v_sub_f32_e32 v0, v5, v95
	v_mul_f32_e32 v0, 0x3fb8aa3b, v0
	v_exp_f32_e32 v98, v0
	v_sub_u32_e32 v0, 63, v7
	v_mad_u64_u32 v[126:127], s[20:21], v0, s84, v[10:11]
	v_sub_f32_e32 v0, v5, v94
	v_mul_f32_e32 v0, 0x3fb8aa3b, v0
	v_exp_f32_e32 v87, v0
	v_or_b32_e32 v0, 7, v12
	v_sub_u32_e32 v7, 63, v0
	v_lshlrev_b32_e32 v0, 2, v0
	v_sub_u32_e32 v0, v104, v0
	ds_read_b32 v92, v92
	ds_read_b32 v96, v96
	ds_read_b32 v0, v0 offset:508
	v_mad_u64_u32 v[12:13], s[20:21], v7, s84, v[10:11]
	ds_read_b32 v93, v126
	ds_read_b32 v97, v12
	v_ashrrev_i32_e32 v15, 31, v14
	s_waitcnt lgkmcnt(2)
	v_sub_f32_e32 v0, v5, v0
	v_mul_f32_e32 v0, 0x3fb8aa3b, v0
	v_pk_mul_f32 v[12:13], v[16:17], v[84:85]
	v_exp_f32_e32 v99, v0
	v_lshlrev_b32_e32 v94, 5, v14
	v_mov_b32_e32 v95, 0
	v_lshl_add_u64 v[94:95], v[8:9], 0, v[94:95]
	v_pk_mul_f32 v[14:15], v[88:89], v[90:91]
	v_and_b32_sdwa v0, v13, v242 dst_sel:DWORD dst_unused:UNUSED_PAD src0_sel:WORD_1 src1_sel:DWORD
	v_and_b32_sdwa v7, v12, v242 dst_sel:DWORD dst_unused:UNUSED_PAD src0_sel:WORD_1 src1_sel:DWORD
	v_add3_u32 v7, v12, v7, s71
	v_add3_u32 v0, v13, v0, s71
	v_and_b32_sdwa v12, v15, v242 dst_sel:DWORD dst_unused:UNUSED_PAD src0_sel:WORD_1 src1_sel:DWORD
	v_and_b32_sdwa v13, v14, v242 dst_sel:DWORD dst_unused:UNUSED_PAD src0_sel:WORD_1 src1_sel:DWORD
	v_add3_u32 v12, v15, v12, s71
	v_add3_u32 v13, v14, v13, s71
	v_and_b32_e32 v12, 0xffff0000, v12
	v_and_b32_e32 v14, 0xffff0000, v13
	v_or_b32_sdwa v13, v12, v0 dst_sel:DWORD dst_unused:UNUSED_PAD src0_sel:DWORD src1_sel:WORD_1
	v_or_b32_sdwa v12, v14, v7 dst_sel:DWORD dst_unused:UNUSED_PAD src0_sel:DWORD src1_sel:WORD_1
	s_waitcnt lgkmcnt(1)
; DI uint4 pack8(const float* f) { uint4 o; o.x = pk2(f[0], f[1]); o.y = pk2(f[2], f[3]); o.z = pk2(f[4], f[5]); o.w = pk2(f[6], f[7]); return o; }
; template <int D> DI void dn_out(float (&x)[64], lf_t Kl, lf_t Ql, lf_t Gn, bf16_t* DW, bf16_t* DQE, bf16_t* DKT, bf16_t* DUT, float* DEG, int item, int t) {
;     ...
;             for (int i = 0; i < 4; ++i) { const int idx = t + 256 * i, dk = idx & 127, pg = idx >> 7; float v[8];
; #pragma unroll
;                 for (int e = 0; e < 8; ++e) { const int pi = 8 * pg + e, n = D ? 63 - pi : pi; v[e] = Kl[n * 132 + dk] * __expf(glast - Gd[n]); }
;                 *(uint4*)(DKT + (((size_t)D * 1152 + item) * 128 + dk) * 64 + 8 * pg) = pack8(v); }
;             if (t == 0) DEG[D * 1152 + item] = __expf(glast);
	v_pk_mul_f32 v[14:15], v[92:93], v[86:87]
	s_waitcnt lgkmcnt(0)
	v_pk_mul_f32 v[16:17], v[96:97], v[98:99]
	v_and_b32_sdwa v0, v15, v242 dst_sel:DWORD dst_unused:UNUSED_PAD src0_sel:WORD_1 src1_sel:DWORD
	v_and_b32_sdwa v7, v14, v242 dst_sel:DWORD dst_unused:UNUSED_PAD src0_sel:WORD_1 src1_sel:DWORD
	v_add3_u32 v7, v14, v7, s71
	v_add3_u32 v0, v15, v0, s71
	v_and_b32_sdwa v14, v17, v242 dst_sel:DWORD dst_unused:UNUSED_PAD src0_sel:WORD_1 src1_sel:DWORD
	v_and_b32_sdwa v15, v16, v242 dst_sel:DWORD dst_unused:UNUSED_PAD src0_sel:WORD_1 src1_sel:DWORD
	v_add3_u32 v14, v17, v14, s71
	v_add3_u32 v15, v16, v15, s71
	v_and_b32_e32 v14, 0xffff0000, v14
	v_and_b32_e32 v16, 0xffff0000, v15
	v_or_b32_sdwa v15, v14, v0 dst_sel:DWORD dst_unused:UNUSED_PAD src0_sel:DWORD src1_sel:WORD_1
	v_or_b32_sdwa v14, v16, v7 dst_sel:DWORD dst_unused:UNUSED_PAD src0_sel:DWORD src1_sel:WORD_1
	global_store_dwordx4 v[94:95], v[12:15], off
	s_nop 1
	v_and_b32_e32 v12, -8, v6
	v_lshlrev_b32_e32 v0, 2, v12
	v_sub_u32_e32 v0, v104, v0
	ds_read_b32 v0, v0 offset:508
	v_sub_u32_e32 v7, 63, v12
	v_mad_u64_u32 v[14:15], s[20:21], v7, s84, v[10:11]
	ds_read_b32 v14, v14
	s_waitcnt lgkmcnt(1)
	v_sub_f32_e32 v0, v5, v0
	v_mul_f32_e32 v0, 0x3fb8aa3b, v0
	v_exp_f32_e32 v16, v0
	v_or_b32_e32 v0, 2, v12
	v_lshlrev_b32_e32 v7, 2, v0
	v_sub_u32_e32 v7, v104, v7
	ds_read2_b32 v[84:85], v7 offset0:127 offset1:128
	v_sub_u32_e32 v7, 62, v12
	v_mad_u64_u32 v[86:87], s[20:21], v7, s84, v[10:11]
	v_sub_u32_e32 v0, 63, v0
	s_waitcnt lgkmcnt(0)
	v_sub_f32_e32 v7, v5, v85
	v_mul_f32_e32 v7, 0x3fb8aa3b, v7
	v_exp_f32_e32 v88, v7
	v_or_b32_e32 v7, 4, v12
	v_lshlrev_b32_e32 v13, 2, v7
	v_sub_u32_e32 v13, v104, v13
	v_mad_u64_u32 v[90:91], s[20:21], v0, s84, v[10:11]
	v_sub_f32_e32 v0, v5, v84
	ds_read2_b32 v[84:85], v13 offset0:127 offset1:128
	v_mul_f32_e32 v0, 0x3fb8aa3b, v0
	v_exp_f32_e32 v17, v0
	v_or_b32_e32 v0, 3, v12
	v_sub_u32_e32 v0, 63, v0
	v_mad_u64_u32 v[92:93], s[20:21], v0, s84, v[10:11]
	s_waitcnt lgkmcnt(0)
	v_sub_f32_e32 v0, v5, v85
	v_mul_f32_e32 v0, 0x3fb8aa3b, v0
	v_exp_f32_e32 v89, v0
	v_sub_u32_e32 v0, 63, v7
	v_or_b32_e32 v7, 6, v12
	v_lshlrev_b32_e32 v13, 2, v7
	v_sub_u32_e32 v13, v104, v13
	ds_read_b32 v86, v86
	ds_read_b32 v15, v90
	ds_read_b32 v87, v92
	ds_read2_b32 v[92:93], v13 offset0:127 offset1:128
	v_mad_u64_u32 v[90:91], s[20:21], v0, s84, v[10:11]
	v_sub_f32_e32 v0, v5, v84
	v_mul_f32_e32 v0, 0x3fb8aa3b, v0
	v_exp_f32_e32 v84, v0
	v_or_b32_e32 v0, 5, v12
	v_sub_u32_e32 v0, 63, v0
	v_mad_u64_u32 v[94:95], s[20:21], v0, s84, v[10:11]
	s_waitcnt lgkmcnt(0)
	v_sub_f32_e32 v0, v5, v93
	v_mul_f32_e32 v0, 0x3fb8aa3b, v0
	v_exp_f32_e32 v96, v0
	v_sub_u32_e32 v0, 63, v7
	v_mad_u64_u32 v[98:99], s[20:21], v0, s84, v[10:11]
	v_sub_f32_e32 v0, v5, v92
	v_mul_f32_e32 v0, 0x3fb8aa3b, v0
	v_exp_f32_e32 v85, v0
	v_or_b32_e32 v0, 7, v6
	v_sub_u32_e32 v6, 63, v0
	v_lshlrev_b32_e32 v0, 2, v0
	v_sub_u32_e32 v0, v104, v0
	ds_read_b32 v90, v90
	ds_read_b32 v94, v94
	ds_read_b32 v0, v0 offset:508
	v_mad_u64_u32 v[6:7], s[20:21], v6, s84, v[10:11]
	ds_read_b32 v91, v98
	ds_read_b32 v95, v6
	v_ashrrev_i32_e32 v13, 31, v12
	s_waitcnt lgkmcnt(2)
	v_sub_f32_e32 v0, v5, v0
	v_pk_mul_f32 v[6:7], v[14:15], v[16:17]
	v_mul_f32_e32 v0, 0x3fb8aa3b, v0
	v_lshlrev_b32_e32 v12, 5, v12
	v_mov_b32_e32 v13, 0
	v_lshl_add_u64 v[12:13], v[8:9], 0, v[12:13]
	v_pk_mul_f32 v[8:9], v[86:87], v[88:89]
	v_and_b32_sdwa v10, v6, v242 dst_sel:DWORD dst_unused:UNUSED_PAD src0_sel:WORD_1 src1_sel:DWORD
	v_exp_f32_e32 v97, v0
	v_and_b32_sdwa v0, v7, v242 dst_sel:DWORD dst_unused:UNUSED_PAD src0_sel:WORD_1 src1_sel:DWORD
	v_add3_u32 v6, v6, v10, s71
	v_and_b32_sdwa v10, v8, v242 dst_sel:DWORD dst_unused:UNUSED_PAD src0_sel:WORD_1 src1_sel:DWORD
	v_add3_u32 v0, v7, v0, s71
	v_and_b32_sdwa v7, v9, v242 dst_sel:DWORD dst_unused:UNUSED_PAD src0_sel:WORD_1 src1_sel:DWORD
	v_add3_u32 v8, v8, v10, s71
	v_add3_u32 v7, v9, v7, s71
	v_and_b32_e32 v8, 0xffff0000, v8
	v_and_b32_e32 v7, 0xffff0000, v7
	v_or_b32_sdwa v6, v8, v6 dst_sel:DWORD dst_unused:UNUSED_PAD src0_sel:DWORD src1_sel:WORD_1
	s_waitcnt lgkmcnt(1)
	v_pk_mul_f32 v[8:9], v[90:91], v[84:85]
	v_or_b32_sdwa v7, v7, v0 dst_sel:DWORD dst_unused:UNUSED_PAD src0_sel:DWORD src1_sel:WORD_1
	s_waitcnt lgkmcnt(0)
	v_pk_mul_f32 v[14:15], v[94:95], v[96:97]
	v_and_b32_sdwa v0, v9, v242 dst_sel:DWORD dst_unused:UNUSED_PAD src0_sel:WORD_1 src1_sel:DWORD
	v_and_b32_sdwa v10, v8, v242 dst_sel:DWORD dst_unused:UNUSED_PAD src0_sel:WORD_1 src1_sel:DWORD
	v_add3_u32 v8, v8, v10, s71
	v_add3_u32 v0, v9, v0, s71
	v_and_b32_sdwa v9, v15, v242 dst_sel:DWORD dst_unused:UNUSED_PAD src0_sel:WORD_1 src1_sel:DWORD
	v_and_b32_sdwa v10, v14, v242 dst_sel:DWORD dst_unused:UNUSED_PAD src0_sel:WORD_1 src1_sel:DWORD
	v_add3_u32 v9, v15, v9, s71
	v_add3_u32 v10, v14, v10, s71
	v_and_b32_e32 v9, 0xffff0000, v9
	v_and_b32_e32 v10, 0xffff0000, v10
	v_or_b32_sdwa v9, v9, v0 dst_sel:DWORD dst_unused:UNUSED_PAD src0_sel:DWORD src1_sel:WORD_1
	v_or_b32_sdwa v8, v10, v8 dst_sel:DWORD dst_unused:UNUSED_PAD src0_sel:DWORD src1_sel:WORD_1
	global_store_dwordx4 v[12:13], v[6:9], off
	s_and_saveexec_b64 s[20:21], vcc
	s_cbranch_execz .LBB0_661
	v_mul_f32_e32 v0, 0x3fb8aa3b, v5
	v_exp_f32_e32 v0, v0
	s_add_u32 s28, s66, s8
	s_addc_u32 s29, s67, s9
	v_mov_b32_e32 v4, 0x2be6b000
	global_store_dword v4, v0, s[28:29] offset:512

; DI unsigned pk2(float lo, float hi) { return f2bf(lo) | (f2bf(hi) << 16); }
; template <int D> DI void dn_out(float (&x)[64], lf_t Kl, lf_t Ql, lf_t Gn, bf16_t* DW, bf16_t* DQE, bf16_t* DKT, bf16_t* DUT, float* DEG, int item, int t) {
;     ...
;             for (int i = 0; i < 4; ++i) { const int idx = t + 256 * i, pi = idx >> 4, seg = idx & 15, n = D ? 63 - pi : pi; const float e = __expf(Gd[n]);
;                 const float4 a0 = *(const float4*)(Ql + n * 132 + seg * 8), a1 = *(const float4*)(Ql + n * 132 + seg * 8 + 4);
;                 uint4 o; o.x = pk2(a0.x * e, a0.y * e); o.y = pk2(a0.z * e, a0.w * e); o.z = pk2(a1.x * e, a1.y * e); o.w = pk2(a1.z * e, a1.w * e);
;                 *(uint4*)(DQE + (((size_t)D * 1152 + item) * 64 + pi) * 128 + seg * 8) = o; }
.LBB0_667:
	s_or_b64 exec, exec, s[20:21]
	v_ashrrev_i32_e32 v12, 4, v4
	v_lshl_add_u32 v0, v12, 2, v104
	ds_read_b32 v2, v0
	v_lshlrev_b32_e32 v0, 5, v4
	v_and_b32_e32 v0, 0x1e0, v0
	v_add_u32_e32 v0, v103, v0
	v_mad_u64_u32 v[10:11], s[20:21], v12, s84, v[0:1]
	ds_read_b128 v[6:9], v10
	s_waitcnt lgkmcnt(1)
	v_mul_f32_e32 v2, 0x3fb8aa3b, v2
	v_ashrrev_i32_e32 v13, 31, v12
	v_exp_f32_e32 v2, v2
	v_lshlrev_b32_e32 v3, 8, v4
	v_and_b32_e32 v14, 15, v12
	v_lshrrev_b32_e32 v15, 4, v12
	v_lshlrev_b32_e32 v14, 4, v14
	v_lshl_add_u32 v14, v15, 12, v14
	v_mov_b32_e32 v15, 0
	v_and_b32_e32 v13, 0xf00, v3
	s_add_u32 s20, s66, s12
	v_or_b32_e32 v14, v14, v13
	s_addc_u32 s21, s67, s13
	v_lshl_add_u64 v[22:23], s[20:21], 0, v[14:15]
	ds_read_b128 v[14:17], v10 offset:16
	s_waitcnt lgkmcnt(1)
	v_mov_b32_e32 v10, v6
	v_mov_b32_e32 v11, v8
	v_pk_mul_f32 v[10:11], v[10:11], v[2:3] op_sel_hi:[1,0]
	v_mov_b32_e32 v8, v7
	v_pk_mul_f32 v[6:7], v[8:9], v[2:3] op_sel_hi:[1,0]
	v_and_b32_sdwa v8, v10, v242 dst_sel:DWORD dst_unused:UNUSED_PAD src0_sel:WORD_1 src1_sel:DWORD
	v_add3_u32 v8, v10, v8, s71
	v_and_b32_sdwa v10, v6, v242 dst_sel:DWORD dst_unused:UNUSED_PAD src0_sel:WORD_1 src1_sel:DWORD
	v_add3_u32 v6, v6, v10, s71
	v_and_b32_sdwa v3, v11, v242 dst_sel:DWORD dst_unused:UNUSED_PAD src0_sel:WORD_1 src1_sel:DWORD
	v_and_b32_sdwa v9, v7, v242 dst_sel:DWORD dst_unused:UNUSED_PAD src0_sel:WORD_1 src1_sel:DWORD
	v_and_b32_e32 v6, 0xffff0000, v6
	v_add3_u32 v3, v11, v3, s71
	v_add3_u32 v7, v7, v9, s71
	v_or_b32_sdwa v6, v6, v8 dst_sel:DWORD dst_unused:UNUSED_PAD src0_sel:DWORD src1_sel:WORD_1
	s_waitcnt lgkmcnt(0)
	v_mov_b32_e32 v8, v14
	v_mov_b32_e32 v9, v16
	v_and_b32_e32 v7, 0xffff0000, v7
	v_pk_mul_f32 v[8:9], v[2:3], v[8:9] op_sel_hi:[0,1]
	v_mov_b32_e32 v16, v15
	v_or_b32_sdwa v7, v7, v3 dst_sel:DWORD dst_unused:UNUSED_PAD src0_sel:DWORD src1_sel:WORD_1
	v_pk_mul_f32 v[2:3], v[2:3], v[16:17] op_sel_hi:[0,1]
	v_and_b32_sdwa v11, v8, v242 dst_sel:DWORD dst_unused:UNUSED_PAD src0_sel:WORD_1 src1_sel:DWORD
	v_add3_u32 v8, v8, v11, s71
	v_and_b32_sdwa v11, v2, v242 dst_sel:DWORD dst_unused:UNUSED_PAD src0_sel:WORD_1 src1_sel:DWORD
	v_add3_u32 v2, v2, v11, s71
	v_and_b32_sdwa v10, v9, v242 dst_sel:DWORD dst_unused:UNUSED_PAD src0_sel:WORD_1 src1_sel:DWORD
	v_and_b32_e32 v2, 0xffff0000, v2
	v_add3_u32 v9, v9, v10, s71
	v_and_b32_sdwa v10, v3, v242 dst_sel:DWORD dst_unused:UNUSED_PAD src0_sel:WORD_1 src1_sel:DWORD
	v_or_b32_sdwa v8, v2, v8 dst_sel:DWORD dst_unused:UNUSED_PAD src0_sel:DWORD src1_sel:WORD_1
	v_add_u32_e32 v2, 0x100, v4
	v_add3_u32 v3, v3, v10, s71
	v_ashrrev_i32_e32 v10, 4, v2
	v_lshl_add_u32 v2, v10, 2, v104
	ds_read_b32 v14, v2
	s_mov_b32 s4, 0x21c6a000
	v_and_b32_e32 v3, 0xffff0000, v3
	v_add_co_u32_e32 v2, vcc, s4, v22
	v_or_b32_sdwa v9, v3, v9 dst_sel:DWORD dst_unused:UNUSED_PAD src0_sel:DWORD src1_sel:WORD_1
	s_nop 0
	v_addc_co_u32_e32 v3, vcc, 0, v23, vcc
	global_store_dwordx4 v[2:3], v[6:9], off
	s_waitcnt lgkmcnt(0)
	v_mul_f32_e32 v2, 0x3fb8aa3b, v14
	v_mad_u64_u32 v[14:15], s[28:29], v10, s84, v[0:1]
	ds_read_b128 v[6:9], v14
	v_ashrrev_i32_e32 v11, 31, v10
	v_exp_f32_e32 v2, v2
	v_and_b32_e32 v16, 15, v10
	v_lshrrev_b32_e32 v17, 4, v10
	v_lshlrev_b32_e32 v16, 4, v16
	v_lshl_add_u32 v16, v17, 12, v16
	v_mov_b32_e32 v17, 0
	v_or_b32_e32 v16, v16, v13
	v_lshl_add_u64 v[26:27], s[20:21], 0, v[16:17]
	ds_read_b128 v[14:17], v14 offset:16
	s_waitcnt lgkmcnt(1)
	v_mov_b32_e32 v23, v8
	v_mov_b32_e32 v8, v7
	v_mov_b32_e32 v22, v6
	v_pk_mul_f32 v[6:7], v[8:9], v[2:3] op_sel_hi:[1,0]
	v_pk_mul_f32 v[22:23], v[22:23], v[2:3] op_sel_hi:[1,0]
	v_and_b32_sdwa v9, v7, v242 dst_sel:DWORD dst_unused:UNUSED_PAD src0_sel:WORD_1 src1_sel:DWORD
	v_and_b32_sdwa v11, v6, v242 dst_sel:DWORD dst_unused:UNUSED_PAD src0_sel:WORD_1 src1_sel:DWORD
	v_and_b32_sdwa v3, v23, v242 dst_sel:DWORD dst_unused:UNUSED_PAD src0_sel:WORD_1 src1_sel:DWORD
	v_and_b32_sdwa v8, v22, v242 dst_sel:DWORD dst_unused:UNUSED_PAD src0_sel:WORD_1 src1_sel:DWORD
	v_add3_u32 v7, v7, v9, s71
	v_add3_u32 v6, v6, v11, s71
	v_add3_u32 v8, v22, v8, s71
	v_add3_u32 v3, v23, v3, s71
	v_and_b32_e32 v7, 0xffff0000, v7
	v_and_b32_e32 v6, 0xffff0000, v6
	v_or_b32_sdwa v23, v7, v3 dst_sel:DWORD dst_unused:UNUSED_PAD src0_sel:DWORD src1_sel:WORD_1
	v_or_b32_sdwa v22, v6, v8 dst_sel:DWORD dst_unused:UNUSED_PAD src0_sel:DWORD src1_sel:WORD_1
	s_waitcnt lgkmcnt(0)
	v_mov_b32_e32 v6, v14
	v_mov_b32_e32 v7, v16
	v_pk_mul_f32 v[6:7], v[2:3], v[6:7] op_sel_hi:[0,1]
	v_mov_b32_e32 v16, v15
	v_pk_mul_f32 v[2:3], v[2:3], v[16:17] op_sel_hi:[0,1]
	v_and_b32_sdwa v9, v6, v242 dst_sel:DWORD dst_unused:UNUSED_PAD src0_sel:WORD_1 src1_sel:DWORD
	v_add3_u32 v6, v6, v9, s71
	v_and_b32_sdwa v9, v2, v242 dst_sel:DWORD dst_unused:UNUSED_PAD src0_sel:WORD_1 src1_sel:DWORD
	v_add3_u32 v2, v2, v9, s71
	v_and_b32_e32 v2, 0xffff0000, v2
	v_or_b32_sdwa v24, v2, v6 dst_sel:DWORD dst_unused:UNUSED_PAD src0_sel:DWORD src1_sel:WORD_1
	v_add_u32_e32 v2, 0x200, v4
	v_and_b32_sdwa v8, v7, v242 dst_sel:DWORD dst_unused:UNUSED_PAD src0_sel:WORD_1 src1_sel:DWORD
	v_ashrrev_i32_e32 v6, 4, v2
	v_add3_u32 v7, v7, v8, s71
	v_and_b32_sdwa v8, v3, v242 dst_sel:DWORD dst_unused:UNUSED_PAD src0_sel:WORD_1 src1_sel:DWORD
	v_lshl_add_u32 v2, v6, 2, v104
	v_add3_u32 v3, v3, v8, s71
	ds_read_b32 v8, v2
	v_and_b32_e32 v3, 0xffff0000, v3
	v_add_co_u32_e32 v2, vcc, s4, v26
	v_or_b32_sdwa v25, v3, v7 dst_sel:DWORD dst_unused:UNUSED_PAD src0_sel:DWORD src1_sel:WORD_1
	s_nop 0
	v_addc_co_u32_e32 v3, vcc, 0, v27, vcc
	global_store_dwordx4 v[2:3], v[22:25], off
	s_waitcnt lgkmcnt(0)
; DI unsigned pk2(float lo, float hi) { return f2bf(lo) | (f2bf(hi) << 16); }
; DI uint4 pack8(const float* f) { uint4 o; o.x = pk2(f[0], f[1]); o.y = pk2(f[2], f[3]); o.z = pk2(f[4], f[5]); o.w = pk2(f[6], f[7]); return o; }
; template <int D> DI void dn_out(float (&x)[64], lf_t Kl, lf_t Ql, lf_t Gn, bf16_t* DW, bf16_t* DQE, bf16_t* DKT, bf16_t* DUT, float* DEG, int item, int t) {
;     ...
;             for (int i = 0; i < 4; ++i) { const int idx = t + 256 * i, pi = idx >> 4, seg = idx & 15, n = D ? 63 - pi : pi; const float e = __expf(Gd[n]);
;                 const float4 a0 = *(const float4*)(Ql + n * 132 + seg * 8), a1 = *(const float4*)(Ql + n * 132 + seg * 8 + 4);
;                 uint4 o; o.x = pk2(a0.x * e, a0.y * e); o.y = pk2(a0.z * e, a0.w * e); o.z = pk2(a1.x * e, a1.y * e); o.w = pk2(a1.z * e, a1.w * e);
;                 *(uint4*)(DQE + (((size_t)D * 1152 + item) * 64 + pi) * 128 + seg * 8) = o; }
; #pragma unroll
;             for (int i = 0; i < 4; ++i) { const int idx = t + 256 * i, dk = idx & 127, pg = idx >> 7; float v[8];
; #pragma unroll
;                 for (int e = 0; e < 8; ++e) { const int pi = 8 * pg + e, n = D ? 63 - pi : pi; v[e] = Kl[n * 132 + dk] * __expf(glast - Gd[n]); }
;                 *(uint4*)(DKT + (((size_t)D * 1152 + item) * 128 + dk) * 64 + 8 * pg) = pack8(v); }
	v_mul_f32_e32 v2, 0x3fb8aa3b, v8
	v_mad_u64_u32 v[8:9], s[28:29], v6, s84, v[0:1]
	ds_read_b128 v[14:17], v8
	v_ashrrev_i32_e32 v7, 31, v6
	v_exp_f32_e32 v2, v2
	v_and_b32_e32 v22, 15, v6
	v_lshrrev_b32_e32 v23, 4, v6
	v_lshlrev_b32_e32 v22, 4, v22
	v_lshl_add_u32 v22, v23, 12, v22
	v_mov_b32_e32 v23, 0
	v_or_b32_e32 v22, v22, v13
	v_lshl_add_u64 v[26:27], s[20:21], 0, v[22:23]
	ds_read_b128 v[22:25], v8 offset:16
	s_waitcnt lgkmcnt(1)
	v_mov_b32_e32 v8, v14
	v_mov_b32_e32 v9, v16
	v_pk_mul_f32 v[8:9], v[8:9], v[2:3] op_sel_hi:[1,0]
	v_mov_b32_e32 v16, v15
	v_pk_mul_f32 v[14:15], v[16:17], v[2:3] op_sel_hi:[1,0]
	v_and_b32_sdwa v3, v9, v242 dst_sel:DWORD dst_unused:UNUSED_PAD src0_sel:WORD_1 src1_sel:DWORD
	v_and_b32_sdwa v7, v8, v242 dst_sel:DWORD dst_unused:UNUSED_PAD src0_sel:WORD_1 src1_sel:DWORD
	v_add3_u32 v7, v8, v7, s71
	v_add3_u32 v3, v9, v3, s71
	v_and_b32_sdwa v8, v15, v242 dst_sel:DWORD dst_unused:UNUSED_PAD src0_sel:WORD_1 src1_sel:DWORD
	v_and_b32_sdwa v9, v14, v242 dst_sel:DWORD dst_unused:UNUSED_PAD src0_sel:WORD_1 src1_sel:DWORD
	v_add3_u32 v8, v15, v8, s71
	v_add3_u32 v9, v14, v9, s71
	v_and_b32_e32 v8, 0xffff0000, v8
	v_and_b32_e32 v9, 0xffff0000, v9
	v_or_b32_sdwa v15, v8, v3 dst_sel:DWORD dst_unused:UNUSED_PAD src0_sel:DWORD src1_sel:WORD_1
	v_or_b32_sdwa v14, v9, v7 dst_sel:DWORD dst_unused:UNUSED_PAD src0_sel:DWORD src1_sel:WORD_1
	s_waitcnt lgkmcnt(0)
	v_mov_b32_e32 v8, v22
	v_mov_b32_e32 v9, v24
	v_pk_mul_f32 v[8:9], v[2:3], v[8:9] op_sel_hi:[0,1]
	v_mov_b32_e32 v24, v23
	v_pk_mul_f32 v[2:3], v[2:3], v[24:25] op_sel_hi:[0,1]
	v_and_b32_sdwa v11, v8, v242 dst_sel:DWORD dst_unused:UNUSED_PAD src0_sel:WORD_1 src1_sel:DWORD
	v_add3_u32 v8, v8, v11, s71
	v_and_b32_sdwa v11, v2, v242 dst_sel:DWORD dst_unused:UNUSED_PAD src0_sel:WORD_1 src1_sel:DWORD
	v_and_b32_sdwa v7, v9, v242 dst_sel:DWORD dst_unused:UNUSED_PAD src0_sel:WORD_1 src1_sel:DWORD
	v_add3_u32 v2, v2, v11, s71
	v_add3_u32 v7, v9, v7, s71
	v_and_b32_sdwa v9, v3, v242 dst_sel:DWORD dst_unused:UNUSED_PAD src0_sel:WORD_1 src1_sel:DWORD
	v_and_b32_e32 v2, 0xffff0000, v2
	v_add3_u32 v3, v3, v9, s71
	v_or_b32_sdwa v16, v2, v8 dst_sel:DWORD dst_unused:UNUSED_PAD src0_sel:DWORD src1_sel:WORD_1
	v_add_u32_e32 v2, 0x300, v4
	v_and_b32_e32 v3, 0xffff0000, v3
	v_ashrrev_i32_e32 v2, 4, v2
	v_or_b32_sdwa v17, v3, v7 dst_sel:DWORD dst_unused:UNUSED_PAD src0_sel:DWORD src1_sel:WORD_1
	v_lshl_add_u32 v3, v2, 2, v104
	ds_read_b32 v7, v3
	v_add_co_u32_e32 v8, vcc, s4, v26
	v_mad_u64_u32 v[22:23], s[28:29], v2, s84, v[0:1]
	s_nop 0
	v_addc_co_u32_e32 v9, vcc, 0, v27, vcc
	global_store_dwordx4 v[8:9], v[14:17], off
	ds_read_b128 v[14:17], v22
	v_ashrrev_i32_e32 v3, 31, v2
	s_waitcnt lgkmcnt(1)
	v_mul_f32_e32 v7, 0x3fb8aa3b, v7
	v_exp_f32_e32 v8, v7
	v_and_b32_e32 v24, 15, v2
	v_lshrrev_b32_e32 v25, 4, v2
	v_lshlrev_b32_e32 v24, 4, v24
	v_lshl_add_u32 v24, v25, 12, v24
	v_mov_b32_e32 v25, 0
	v_or_b32_e32 v24, v24, v13
	v_lshl_add_u64 v[26:27], s[20:21], 0, v[24:25]
	ds_read_b128 v[22:25], v22 offset:16
	s_waitcnt lgkmcnt(1)
	v_mov_b32_e32 v29, v16
	v_mov_b32_e32 v16, v15
	v_mov_b32_e32 v28, v14
	v_pk_mul_f32 v[14:15], v[16:17], v[8:9] op_sel_hi:[1,0]
	v_pk_mul_f32 v[28:29], v[28:29], v[8:9] op_sel_hi:[1,0]
	v_and_b32_sdwa v9, v14, v242 dst_sel:DWORD dst_unused:UNUSED_PAD src0_sel:WORD_1 src1_sel:DWORD
	v_and_b32_sdwa v3, v28, v242 dst_sel:DWORD dst_unused:UNUSED_PAD src0_sel:WORD_1 src1_sel:DWORD
	v_add3_u32 v9, v14, v9, s71
	v_add3_u32 v3, v28, v3, s71
	v_and_b32_sdwa v7, v15, v242 dst_sel:DWORD dst_unused:UNUSED_PAD src0_sel:WORD_1 src1_sel:DWORD
	v_and_b32_e32 v9, 0xffff0000, v9
	s_waitcnt lgkmcnt(0)
	v_mov_b32_e32 v16, v22
	v_mov_b32_e32 v17, v24
	v_mov_b32_e32 v24, v23
	v_and_b32_sdwa v0, v29, v242 dst_sel:DWORD dst_unused:UNUSED_PAD src0_sel:WORD_1 src1_sel:DWORD
	v_add3_u32 v7, v15, v7, s71
	v_or_b32_sdwa v14, v9, v3 dst_sel:DWORD dst_unused:UNUSED_PAD src0_sel:DWORD src1_sel:WORD_1
	v_pk_mul_f32 v[16:17], v[8:9], v[16:17] op_sel_hi:[0,1]
	v_pk_mul_f32 v[8:9], v[8:9], v[24:25] op_sel_hi:[0,1]
	v_add3_u32 v0, v29, v0, s71
	v_and_b32_e32 v7, 0xffff0000, v7
	v_and_b32_sdwa v11, v8, v242 dst_sel:DWORD dst_unused:UNUSED_PAD src0_sel:WORD_1 src1_sel:DWORD
	v_or_b32_sdwa v15, v7, v0 dst_sel:DWORD dst_unused:UNUSED_PAD src0_sel:DWORD src1_sel:WORD_1
	v_and_b32_sdwa v3, v16, v242 dst_sel:DWORD dst_unused:UNUSED_PAD src0_sel:WORD_1 src1_sel:DWORD
	v_and_b32_sdwa v7, v9, v242 dst_sel:DWORD dst_unused:UNUSED_PAD src0_sel:WORD_1 src1_sel:DWORD
	v_add3_u32 v8, v8, v11, s71
	v_and_b32_sdwa v0, v17, v242 dst_sel:DWORD dst_unused:UNUSED_PAD src0_sel:WORD_1 src1_sel:DWORD
	v_add3_u32 v3, v16, v3, s71
	v_add3_u32 v7, v9, v7, s71
	v_and_b32_e32 v8, 0xffff0000, v8
	ds_read_b32 v5, v104 offset:252
	v_add3_u32 v0, v17, v0, s71
	v_and_b32_e32 v7, 0xffff0000, v7
	v_or_b32_sdwa v16, v8, v3 dst_sel:DWORD dst_unused:UNUSED_PAD src0_sel:DWORD src1_sel:WORD_1
	v_add_co_u32_e32 v8, vcc, s4, v26
	v_or_b32_sdwa v17, v7, v0 dst_sel:DWORD dst_unused:UNUSED_PAD src0_sel:DWORD src1_sel:WORD_1
	s_nop 0
	v_addc_co_u32_e32 v9, vcc, 0, v27, vcc
	global_store_dwordx4 v[8:9], v[14:17], off
	v_and_b32_e32 v0, 0x7f, v4
	v_lshl_add_u32 v8, v0, 2, v100
	v_and_b32_e32 v14, -8, v12
	v_lshl_add_u32 v3, v14, 2, v104
	v_mad_u64_u32 v[16:17], s[28:29], v14, s84, v[8:9]
	ds_read2_b32 v[22:23], v3 offset1:1
	ds_read2_b32 v[24:25], v16 offset1:132
	ds_read2_b32 v[26:27], v3 offset0:2 offset1:3
	ds_read2_b32 v[28:29], v3 offset0:4 offset1:5
	ds_read_b32 v3, v3 offset:24
	s_waitcnt lgkmcnt(4)
	v_sub_f32_e32 v7, v5, v22
	v_mul_f32_e32 v7, 0x3fb8aa3b, v7
	v_exp_f32_e32 v22, v7
	v_sub_f32_e32 v7, v5, v23
	v_mul_f32_e32 v7, 0x3fb8aa3b, v7
	v_exp_f32_e32 v30, v7
	v_add_u32_e32 v7, 0x400, v16
	ds_read2_b32 v[32:33], v7 offset0:8 offset1:140
	s_waitcnt lgkmcnt(3)
; DI uint4 pack8(const float* f) { uint4 o; o.x = pk2(f[0], f[1]); o.y = pk2(f[2], f[3]); o.z = pk2(f[4], f[5]); o.w = pk2(f[6], f[7]); return o; }
; template <int D> DI void dn_out(float (&x)[64], lf_t Kl, lf_t Ql, lf_t Gn, bf16_t* DW, bf16_t* DQE, bf16_t* DKT, bf16_t* DUT, float* DEG, int item, int t) {
;     ...
;             for (int i = 0; i < 4; ++i) { const int idx = t + 256 * i, dk = idx & 127, pg = idx >> 7; float v[8];
; #pragma unroll
;                 for (int e = 0; e < 8; ++e) { const int pi = 8 * pg + e, n = D ? 63 - pi : pi; v[e] = Kl[n * 132 + dk] * __expf(glast - Gd[n]); }
;                 *(uint4*)(DKT + (((size_t)D * 1152 + item) * 128 + dk) * 64 + 8 * pg) = pack8(v); }
	v_sub_f32_e32 v7, v5, v26
	v_mul_f32_e32 v7, 0x3fb8aa3b, v7
	v_exp_f32_e32 v23, v7
	v_sub_f32_e32 v7, v5, v27
	v_mul_f32_e32 v7, 0x3fb8aa3b, v7
	v_exp_f32_e32 v31, v7
	v_add_u32_e32 v7, 0x800, v16
	ds_read2_b32 v[26:27], v7 offset0:16 offset1:148
	s_waitcnt lgkmcnt(3)
	v_sub_f32_e32 v7, v5, v28
	v_mul_f32_e32 v7, 0x3fb8aa3b, v7
	v_exp_f32_e32 v28, v7
	v_sub_f32_e32 v7, v5, v29
	v_mul_f32_e32 v7, 0x3fb8aa3b, v7
	v_exp_f32_e32 v34, v7
	v_or_b32_e32 v7, 7, v12
	v_lshl_add_u32 v9, v7, 2, v104
	ds_read_b32 v9, v9
	s_waitcnt lgkmcnt(3)
	v_sub_f32_e32 v3, v5, v3
	v_mul_f32_e32 v3, 0x3fb8aa3b, v3
	v_exp_f32_e32 v29, v3
	v_ashrrev_i32_e32 v15, 31, v14
	s_waitcnt lgkmcnt(0)
	v_mad_u64_u32 v[12:13], s[28:29], v7, s84, v[8:9]
	v_sub_f32_e32 v3, v5, v9
	v_and_b32_e32 v13, 15, v0
	v_lshrrev_b32_e32 v0, 4, v0
	v_lshlrev_b32_e32 v0, 11, v0
	v_lshl_add_u32 v0, v13, 4, v0
	ds_read_b32 v17, v16 offset:3168
	ds_read_b32 v37, v12
	v_mul_f32_e32 v3, 0x3fb8aa3b, v3
	v_lshlrev_b32_e32 v12, 5, v14
	v_mov_b32_e32 v13, 0
	v_lshl_add_u64 v[12:13], v[0:1], 0, v[12:13]
	v_exp_f32_e32 v35, v3
	v_lshl_add_u64 v[38:39], s[20:21], 0, v[12:13]
	v_mov_b32_e32 v13, v32
	v_mov_b32_e32 v32, v25
	v_mov_b32_e32 v12, v24
	v_pk_mul_f32 v[14:15], v[32:33], v[30:31]
	v_pk_mul_f32 v[12:13], v[12:13], v[22:23]
	v_and_b32_sdwa v9, v15, v242 dst_sel:DWORD dst_unused:UNUSED_PAD src0_sel:WORD_1 src1_sel:DWORD
	v_and_b32_sdwa v11, v14, v242 dst_sel:DWORD dst_unused:UNUSED_PAD src0_sel:WORD_1 src1_sel:DWORD
	v_and_b32_sdwa v3, v13, v242 dst_sel:DWORD dst_unused:UNUSED_PAD src0_sel:WORD_1 src1_sel:DWORD
	v_and_b32_sdwa v7, v12, v242 dst_sel:DWORD dst_unused:UNUSED_PAD src0_sel:WORD_1 src1_sel:DWORD
	v_add3_u32 v9, v15, v9, s71
	v_add3_u32 v11, v14, v11, s71
	v_mov_b32_e32 v16, v26
	v_mov_b32_e32 v36, v27
	v_add3_u32 v7, v12, v7, s71
	v_add3_u32 v3, v13, v3, s71
	v_and_b32_e32 v9, 0xffff0000, v9
	v_and_b32_e32 v11, 0xffff0000, v11
	s_waitcnt lgkmcnt(1)
	v_pk_mul_f32 v[14:15], v[16:17], v[28:29]
	s_waitcnt lgkmcnt(0)
	v_pk_mul_f32 v[16:17], v[36:37], v[34:35]
	v_or_b32_sdwa v13, v9, v3 dst_sel:DWORD dst_unused:UNUSED_PAD src0_sel:DWORD src1_sel:WORD_1
	v_or_b32_sdwa v12, v11, v7 dst_sel:DWORD dst_unused:UNUSED_PAD src0_sel:DWORD src1_sel:WORD_1
	v_and_b32_sdwa v9, v17, v242 dst_sel:DWORD dst_unused:UNUSED_PAD src0_sel:WORD_1 src1_sel:DWORD
	v_and_b32_sdwa v11, v16, v242 dst_sel:DWORD dst_unused:UNUSED_PAD src0_sel:WORD_1 src1_sel:DWORD
	v_and_b32_sdwa v3, v15, v242 dst_sel:DWORD dst_unused:UNUSED_PAD src0_sel:WORD_1 src1_sel:DWORD
	v_and_b32_sdwa v7, v14, v242 dst_sel:DWORD dst_unused:UNUSED_PAD src0_sel:WORD_1 src1_sel:DWORD
	v_add3_u32 v9, v17, v9, s71
	v_add3_u32 v11, v16, v11, s71
	s_mov_b32 s4, 0x2406a000
	v_add3_u32 v7, v14, v7, s71
	v_add3_u32 v3, v15, v3, s71
	v_and_b32_e32 v9, 0xffff0000, v9
	v_and_b32_e32 v11, 0xffff0000, v11
	v_add_co_u32_e32 v16, vcc, s4, v38
	v_or_b32_sdwa v15, v9, v3 dst_sel:DWORD dst_unused:UNUSED_PAD src0_sel:DWORD src1_sel:WORD_1
	v_or_b32_sdwa v14, v11, v7 dst_sel:DWORD dst_unused:UNUSED_PAD src0_sel:DWORD src1_sel:WORD_1
	v_addc_co_u32_e32 v17, vcc, 0, v39, vcc
	global_store_dwordx4 v[16:17], v[12:15], off
	s_nop 1
	v_and_b32_e32 v12, -8, v10
	v_lshl_add_u32 v3, v12, 2, v104
	v_mad_u64_u32 v[14:15], s[28:29], v12, s84, v[8:9]
	ds_read2_b32 v[16:17], v3 offset1:1
	ds_read2_b32 v[22:23], v14 offset1:132
	ds_read2_b32 v[24:25], v3 offset0:2 offset1:3
	ds_read2_b32 v[26:27], v3 offset0:4 offset1:5
	ds_read_b32 v3, v3 offset:24
	s_waitcnt lgkmcnt(4)
	v_sub_f32_e32 v7, v5, v16
	v_mul_f32_e32 v7, 0x3fb8aa3b, v7
	v_exp_f32_e32 v16, v7
	v_sub_f32_e32 v7, v5, v17
	v_mul_f32_e32 v7, 0x3fb8aa3b, v7
	v_exp_f32_e32 v28, v7
	v_add_u32_e32 v7, 0x400, v14
	ds_read2_b32 v[30:31], v7 offset0:8 offset1:140
	s_waitcnt lgkmcnt(3)
	v_sub_f32_e32 v7, v5, v24
	v_mul_f32_e32 v7, 0x3fb8aa3b, v7
	v_exp_f32_e32 v17, v7
	v_sub_f32_e32 v7, v5, v25
	v_mul_f32_e32 v7, 0x3fb8aa3b, v7
	v_exp_f32_e32 v29, v7
	v_add_u32_e32 v7, 0x800, v14
	ds_read2_b32 v[24:25], v7 offset0:16 offset1:148
	s_waitcnt lgkmcnt(3)
	v_sub_f32_e32 v7, v5, v26
	v_mul_f32_e32 v7, 0x3fb8aa3b, v7
	v_exp_f32_e32 v26, v7
	v_sub_f32_e32 v7, v5, v27
	v_mul_f32_e32 v7, 0x3fb8aa3b, v7
	v_exp_f32_e32 v32, v7
	v_or_b32_e32 v7, 7, v10
	v_lshl_add_u32 v9, v7, 2, v104
	ds_read_b32 v9, v9
	s_waitcnt lgkmcnt(3)
	v_sub_f32_e32 v3, v5, v3
	v_ashrrev_i32_e32 v13, 31, v12
	ds_read_b32 v15, v14 offset:3168
	v_mul_f32_e32 v3, 0x3fb8aa3b, v3
	s_waitcnt lgkmcnt(1)
	v_mad_u64_u32 v[10:11], s[28:29], v7, s84, v[8:9]
	ds_read_b32 v35, v10
	v_lshlrev_b32_e32 v10, 5, v12
	v_mov_b32_e32 v11, 0
	v_lshl_add_u64 v[10:11], v[0:1], 0, v[10:11]
	v_exp_f32_e32 v27, v3
	v_sub_f32_e32 v3, v5, v9
	v_lshl_add_u64 v[36:37], s[20:21], 0, v[10:11]
	v_mov_b32_e32 v10, v22
	v_mov_b32_e32 v11, v30
	v_mul_f32_e32 v3, 0x3fb8aa3b, v3
	v_pk_mul_f32 v[10:11], v[10:11], v[16:17]
	v_mov_b32_e32 v30, v23
	v_exp_f32_e32 v33, v3
	v_pk_mul_f32 v[12:13], v[30:31], v[28:29]
	v_and_b32_sdwa v7, v10, v242 dst_sel:DWORD dst_unused:UNUSED_PAD src0_sel:WORD_1 src1_sel:DWORD
	v_add3_u32 v7, v10, v7, s71
	v_and_b32_sdwa v10, v12, v242 dst_sel:DWORD dst_unused:UNUSED_PAD src0_sel:WORD_1 src1_sel:DWORD
	v_and_b32_sdwa v9, v13, v242 dst_sel:DWORD dst_unused:UNUSED_PAD src0_sel:WORD_1 src1_sel:DWORD
	v_add3_u32 v10, v12, v10, s71
	v_mov_b32_e32 v14, v24
	v_and_b32_sdwa v3, v11, v242 dst_sel:DWORD dst_unused:UNUSED_PAD src0_sel:WORD_1 src1_sel:DWORD
	v_add3_u32 v9, v13, v9, s71
	v_and_b32_e32 v10, 0xffff0000, v10
	s_waitcnt lgkmcnt(1)
	v_pk_mul_f32 v[12:13], v[14:15], v[26:27]
	v_mov_b32_e32 v34, v25
	v_add3_u32 v3, v11, v3, s71
	v_and_b32_e32 v9, 0xffff0000, v9
	v_or_b32_sdwa v10, v10, v7 dst_sel:DWORD dst_unused:UNUSED_PAD src0_sel:DWORD src1_sel:WORD_1
	s_waitcnt lgkmcnt(0)
; DI uint4 pack8(const float* f) { uint4 o; o.x = pk2(f[0], f[1]); o.y = pk2(f[2], f[3]); o.z = pk2(f[4], f[5]); o.w = pk2(f[6], f[7]); return o; }
; template <int D> DI void dn_out(float (&x)[64], lf_t Kl, lf_t Ql, lf_t Gn, bf16_t* DW, bf16_t* DQE, bf16_t* DKT, bf16_t* DUT, float* DEG, int item, int t) {
;     ...
;             for (int i = 0; i < 4; ++i) { const int idx = t + 256 * i, dk = idx & 127, pg = idx >> 7; float v[8];
; #pragma unroll
;                 for (int e = 0; e < 8; ++e) { const int pi = 8 * pg + e, n = D ? 63 - pi : pi; v[e] = Kl[n * 132 + dk] * __expf(glast - Gd[n]); }
;                 *(uint4*)(DKT + (((size_t)D * 1152 + item) * 128 + dk) * 64 + 8 * pg) = pack8(v); }
	v_pk_mul_f32 v[14:15], v[34:35], v[32:33]
	v_and_b32_sdwa v7, v12, v242 dst_sel:DWORD dst_unused:UNUSED_PAD src0_sel:WORD_1 src1_sel:DWORD
	v_or_b32_sdwa v11, v9, v3 dst_sel:DWORD dst_unused:UNUSED_PAD src0_sel:DWORD src1_sel:WORD_1
	v_add3_u32 v7, v12, v7, s71
	v_and_b32_sdwa v9, v15, v242 dst_sel:DWORD dst_unused:UNUSED_PAD src0_sel:WORD_1 src1_sel:DWORD
	v_and_b32_sdwa v12, v14, v242 dst_sel:DWORD dst_unused:UNUSED_PAD src0_sel:WORD_1 src1_sel:DWORD
	v_and_b32_sdwa v3, v13, v242 dst_sel:DWORD dst_unused:UNUSED_PAD src0_sel:WORD_1 src1_sel:DWORD
	v_add3_u32 v9, v15, v9, s71
	v_add3_u32 v12, v14, v12, s71
	v_add3_u32 v3, v13, v3, s71
	v_and_b32_e32 v9, 0xffff0000, v9
	v_and_b32_e32 v12, 0xffff0000, v12
	v_add_co_u32_e32 v14, vcc, s4, v36
	v_or_b32_sdwa v13, v9, v3 dst_sel:DWORD dst_unused:UNUSED_PAD src0_sel:DWORD src1_sel:WORD_1
	v_or_b32_sdwa v12, v12, v7 dst_sel:DWORD dst_unused:UNUSED_PAD src0_sel:DWORD src1_sel:WORD_1
	v_addc_co_u32_e32 v15, vcc, 0, v37, vcc
	global_store_dwordx4 v[14:15], v[10:13], off
	s_nop 1
	v_and_b32_e32 v10, -8, v6
	v_lshl_add_u32 v3, v10, 2, v104
	v_mad_u64_u32 v[12:13], s[28:29], v10, s84, v[8:9]
	ds_read2_b32 v[14:15], v3 offset1:1
	ds_read2_b32 v[16:17], v12 offset1:132
	ds_read2_b32 v[22:23], v3 offset0:2 offset1:3
	ds_read2_b32 v[24:25], v3 offset0:4 offset1:5
	ds_read_b32 v3, v3 offset:24
	s_waitcnt lgkmcnt(4)
	v_sub_f32_e32 v7, v5, v14
	v_mul_f32_e32 v7, 0x3fb8aa3b, v7
	v_exp_f32_e32 v14, v7
	v_sub_f32_e32 v7, v5, v15
	v_mul_f32_e32 v7, 0x3fb8aa3b, v7
	v_exp_f32_e32 v26, v7
	v_add_u32_e32 v7, 0x400, v12
	ds_read2_b32 v[28:29], v7 offset0:8 offset1:140
	s_waitcnt lgkmcnt(3)
	v_sub_f32_e32 v7, v5, v22
	v_mul_f32_e32 v7, 0x3fb8aa3b, v7
	v_exp_f32_e32 v15, v7
	v_sub_f32_e32 v7, v5, v23
	v_or_b32_e32 v6, 7, v6
	v_mul_f32_e32 v7, 0x3fb8aa3b, v7
	v_lshl_add_u32 v9, v6, 2, v104
	v_exp_f32_e32 v27, v7
	v_add_u32_e32 v7, 0x800, v12
	ds_read_b32 v9, v9
	ds_read2_b32 v[22:23], v7 offset0:16 offset1:148
	s_waitcnt lgkmcnt(4)
	v_sub_f32_e32 v7, v5, v24
	v_ashrrev_i32_e32 v11, 31, v10
	v_mul_f32_e32 v7, 0x3fb8aa3b, v7
	v_lshlrev_b32_e32 v10, 5, v10
	v_mov_b32_e32 v11, 0
	v_lshl_add_u64 v[10:11], v[0:1], 0, v[10:11]
	v_exp_f32_e32 v24, v7
	v_sub_f32_e32 v7, v5, v25
	s_waitcnt lgkmcnt(3)
	v_sub_f32_e32 v3, v5, v3
	v_lshl_add_u64 v[32:33], s[20:21], 0, v[10:11]
	v_mov_b32_e32 v10, v16
	s_waitcnt lgkmcnt(2)
	v_mov_b32_e32 v11, v28
	v_mul_f32_e32 v7, 0x3fb8aa3b, v7
	v_mul_f32_e32 v3, 0x3fb8aa3b, v3
	v_pk_mul_f32 v[10:11], v[10:11], v[14:15]
	v_mov_b32_e32 v28, v17
	v_exp_f32_e32 v30, v7
	ds_read_b32 v7, v12 offset:3168
	v_exp_f32_e32 v25, v3
	s_waitcnt lgkmcnt(2)
	v_mad_u64_u32 v[12:13], s[28:29], v6, s84, v[8:9]
	v_sub_f32_e32 v3, v5, v9
	v_pk_mul_f32 v[14:15], v[28:29], v[26:27]
	v_and_b32_sdwa v6, v10, v242 dst_sel:DWORD dst_unused:UNUSED_PAD src0_sel:WORD_1 src1_sel:DWORD
	ds_read_b32 v13, v12
	v_mul_f32_e32 v3, 0x3fb8aa3b, v3
	v_add3_u32 v6, v10, v6, s71
	v_and_b32_sdwa v10, v14, v242 dst_sel:DWORD dst_unused:UNUSED_PAD src0_sel:WORD_1 src1_sel:DWORD
	v_exp_f32_e32 v31, v3
	v_add3_u32 v10, v14, v10, s71
	v_and_b32_sdwa v9, v15, v242 dst_sel:DWORD dst_unused:UNUSED_PAD src0_sel:WORD_1 src1_sel:DWORD
	v_and_b32_e32 v10, 0xffff0000, v10
	v_and_b32_sdwa v3, v11, v242 dst_sel:DWORD dst_unused:UNUSED_PAD src0_sel:WORD_1 src1_sel:DWORD
	v_add3_u32 v9, v15, v9, s71
	v_or_b32_sdwa v10, v10, v6 dst_sel:DWORD dst_unused:UNUSED_PAD src0_sel:DWORD src1_sel:WORD_1
	s_waitcnt lgkmcnt(2)
	v_mov_b32_e32 v6, v22
	v_add3_u32 v3, v11, v3, s71
	v_and_b32_e32 v9, 0xffff0000, v9
	s_waitcnt lgkmcnt(1)
	v_pk_mul_f32 v[6:7], v[6:7], v[24:25]
	v_mov_b32_e32 v12, v23
	v_or_b32_sdwa v11, v9, v3 dst_sel:DWORD dst_unused:UNUSED_PAD src0_sel:DWORD src1_sel:WORD_1
	s_waitcnt lgkmcnt(0)
; DI uint4 pack8(const float* f) { uint4 o; o.x = pk2(f[0], f[1]); o.y = pk2(f[2], f[3]); o.z = pk2(f[4], f[5]); o.w = pk2(f[6], f[7]); return o; }
; template <int D> DI void dn_out(float (&x)[64], lf_t Kl, lf_t Ql, lf_t Gn, bf16_t* DW, bf16_t* DQE, bf16_t* DKT, bf16_t* DUT, float* DEG, int item, int t) {
;     ...
;             for (int i = 0; i < 4; ++i) { const int idx = t + 256 * i, dk = idx & 127, pg = idx >> 7; float v[8];
; #pragma unroll
;                 for (int e = 0; e < 8; ++e) { const int pi = 8 * pg + e, n = D ? 63 - pi : pi; v[e] = Kl[n * 132 + dk] * __expf(glast - Gd[n]); }
;                 *(uint4*)(DKT + (((size_t)D * 1152 + item) * 128 + dk) * 64 + 8 * pg) = pack8(v); }
;             if (t == 0) DEG[D * 1152 + item] = __expf(glast);
	v_pk_mul_f32 v[12:13], v[12:13], v[30:31]
	v_and_b32_sdwa v9, v6, v242 dst_sel:DWORD dst_unused:UNUSED_PAD src0_sel:WORD_1 src1_sel:DWORD
	v_and_b32_sdwa v3, v7, v242 dst_sel:DWORD dst_unused:UNUSED_PAD src0_sel:WORD_1 src1_sel:DWORD
	v_add3_u32 v6, v6, v9, s71
	v_and_b32_sdwa v9, v12, v242 dst_sel:DWORD dst_unused:UNUSED_PAD src0_sel:WORD_1 src1_sel:DWORD
	v_add3_u32 v3, v7, v3, s71
	v_and_b32_sdwa v7, v13, v242 dst_sel:DWORD dst_unused:UNUSED_PAD src0_sel:WORD_1 src1_sel:DWORD
	v_add3_u32 v9, v12, v9, s71
	v_add3_u32 v7, v13, v7, s71
	v_and_b32_e32 v9, 0xffff0000, v9
	v_and_b32_e32 v7, 0xffff0000, v7
	v_or_b32_sdwa v12, v9, v6 dst_sel:DWORD dst_unused:UNUSED_PAD src0_sel:DWORD src1_sel:WORD_1
	v_add_co_u32_e32 v6, vcc, s4, v32
	v_or_b32_sdwa v13, v7, v3 dst_sel:DWORD dst_unused:UNUSED_PAD src0_sel:DWORD src1_sel:WORD_1
	s_nop 0
	v_addc_co_u32_e32 v7, vcc, 0, v33, vcc
	global_store_dwordx4 v[6:7], v[10:13], off
	v_and_b32_e32 v6, -8, v2
	v_lshl_add_u32 v3, v6, 2, v104
	v_mad_u64_u32 v[10:11], s[28:29], v6, s84, v[8:9]
	ds_read2_b32 v[12:13], v3 offset1:1
	ds_read2_b32 v[14:15], v10 offset1:132
	ds_read2_b32 v[16:17], v3 offset0:2 offset1:3
	ds_read2_b32 v[22:23], v3 offset0:4 offset1:5
	ds_read_b32 v7, v3 offset:24
	s_waitcnt lgkmcnt(4)
	v_sub_f32_e32 v3, v5, v12
	v_mul_f32_e32 v3, 0x3fb8aa3b, v3
	v_exp_f32_e32 v12, v3
	v_sub_f32_e32 v3, v5, v13
	v_mul_f32_e32 v3, 0x3fb8aa3b, v3
	v_exp_f32_e32 v24, v3
	v_add_u32_e32 v3, 0x400, v10
	ds_read2_b32 v[26:27], v3 offset0:8 offset1:140
	s_waitcnt lgkmcnt(3)
	v_sub_f32_e32 v3, v5, v16
	v_mul_f32_e32 v3, 0x3fb8aa3b, v3
	v_exp_f32_e32 v13, v3
	v_sub_f32_e32 v3, v5, v17
	v_mul_f32_e32 v3, 0x3fb8aa3b, v3
	v_exp_f32_e32 v25, v3
	v_add_u32_e32 v3, 0x800, v10
	ds_read2_b32 v[16:17], v3 offset0:16 offset1:148
	s_waitcnt lgkmcnt(3)
	v_sub_f32_e32 v3, v5, v22
	v_mul_f32_e32 v3, 0x3fb8aa3b, v3
	v_exp_f32_e32 v22, v3
	v_sub_f32_e32 v3, v5, v23
	v_or_b32_e32 v2, 7, v2
	v_mul_f32_e32 v3, 0x3fb8aa3b, v3
	v_lshl_add_u32 v9, v2, 2, v104
	v_exp_f32_e32 v28, v3
	ds_read_b32 v3, v10 offset:3168
	ds_read_b32 v10, v9
	s_waitcnt lgkmcnt(4)
	v_sub_f32_e32 v7, v5, v7
	v_mul_f32_e32 v7, 0x3fb8aa3b, v7
	v_exp_f32_e32 v23, v7
	v_ashrrev_i32_e32 v7, 31, v6
	v_lshlrev_b32_e32 v6, 5, v6
	v_mov_b32_e32 v7, 0
	v_lshl_add_u64 v[6:7], v[0:1], 0, v[6:7]
	v_mad_u64_u32 v[8:9], s[28:29], v2, s84, v[8:9]
	s_waitcnt lgkmcnt(0)
	v_sub_f32_e32 v2, v5, v10
	v_lshl_add_u64 v[10:11], s[20:21], 0, v[6:7]
	v_mov_b32_e32 v6, v14
	v_mov_b32_e32 v7, v26
	v_mul_f32_e32 v2, 0x3fb8aa3b, v2
	v_pk_mul_f32 v[6:7], v[6:7], v[12:13]
	v_mov_b32_e32 v26, v15
	v_exp_f32_e32 v29, v2
	v_pk_mul_f32 v[12:13], v[26:27], v[24:25]
	v_and_b32_sdwa v0, v7, v242 dst_sel:DWORD dst_unused:UNUSED_PAD src0_sel:WORD_1 src1_sel:DWORD
	v_and_b32_sdwa v2, v6, v242 dst_sel:DWORD dst_unused:UNUSED_PAD src0_sel:WORD_1 src1_sel:DWORD
	ds_read_b32 v9, v8
	v_add3_u32 v2, v6, v2, s71
	v_add3_u32 v0, v7, v0, s71
	v_and_b32_sdwa v6, v13, v242 dst_sel:DWORD dst_unused:UNUSED_PAD src0_sel:WORD_1 src1_sel:DWORD
	v_and_b32_sdwa v7, v12, v242 dst_sel:DWORD dst_unused:UNUSED_PAD src0_sel:WORD_1 src1_sel:DWORD
	v_add3_u32 v6, v13, v6, s71
	v_add3_u32 v7, v12, v7, s71
	v_and_b32_e32 v6, 0xffff0000, v6
	v_and_b32_e32 v8, 0xffff0000, v7
	v_or_b32_sdwa v7, v6, v0 dst_sel:DWORD dst_unused:UNUSED_PAD src0_sel:DWORD src1_sel:WORD_1
	v_or_b32_sdwa v6, v8, v2 dst_sel:DWORD dst_unused:UNUSED_PAD src0_sel:DWORD src1_sel:WORD_1
	v_mov_b32_e32 v2, v16
	v_pk_mul_f32 v[2:3], v[2:3], v[22:23]
	v_mov_b32_e32 v8, v17
	s_waitcnt lgkmcnt(0)
	v_pk_mul_f32 v[8:9], v[8:9], v[28:29]
	v_and_b32_sdwa v12, v2, v242 dst_sel:DWORD dst_unused:UNUSED_PAD src0_sel:WORD_1 src1_sel:DWORD
	v_and_b32_sdwa v0, v3, v242 dst_sel:DWORD dst_unused:UNUSED_PAD src0_sel:WORD_1 src1_sel:DWORD
	v_add3_u32 v2, v2, v12, s71
	v_and_b32_sdwa v12, v8, v242 dst_sel:DWORD dst_unused:UNUSED_PAD src0_sel:WORD_1 src1_sel:DWORD
	v_add3_u32 v0, v3, v0, s71
	v_and_b32_sdwa v3, v9, v242 dst_sel:DWORD dst_unused:UNUSED_PAD src0_sel:WORD_1 src1_sel:DWORD
	v_add3_u32 v8, v8, v12, s71
	v_add3_u32 v3, v9, v3, s71
	v_and_b32_e32 v8, 0xffff0000, v8
	v_and_b32_e32 v3, 0xffff0000, v3
	v_or_b32_sdwa v8, v8, v2 dst_sel:DWORD dst_unused:UNUSED_PAD src0_sel:DWORD src1_sel:WORD_1
	v_add_co_u32_e32 v2, vcc, 0x2406a000, v10
	v_or_b32_sdwa v9, v3, v0 dst_sel:DWORD dst_unused:UNUSED_PAD src0_sel:DWORD src1_sel:WORD_1
	s_nop 0
	v_addc_co_u32_e32 v3, vcc, 0, v11, vcc
	v_cmp_eq_u32_e32 vcc, 0, v4
	global_store_dwordx4 v[2:3], v[6:9], off
	s_and_saveexec_b64 s[20:21], vcc
	s_cbranch_execz .LBB0_474
	v_mul_f32_e32 v0, 0x3fb8aa3b, v5
	v_exp_f32_e32 v0, v0
	s_add_u32 s28, s66, s8
	s_addc_u32 s29, s67, s9
	v_mov_b32_e32 v2, 0x2be6a000
	global_store_dword v2, v0, s[28:29]
	s_branch .LBB0_474
